# write-through sc1 on all dwordx4 phase-output stores (cheaper L2 writeback at grid barriers)
# speedup vs baseline: 1.0046x; 1.0046x over previous
; #define GAS __attribute__((address_space(1)))
; #define LAS __attribute__((address_space(3)))
; __device__ __forceinline__ void p0_transpose_item(const float* W, int K, int N, bf16* WT, int conv, LAS float* scrf, int item, int lane, const float* gk) {
;     ...
;     int dn0 = n0;
;     if (conv) { const int part = n0 >> 10, ch = n0 & 1023, pn = ch >> 6; const int slot = (part == 0) ? 1 : (part == 1) ? 0 : part; dn0 = 256 * pn + 64 * slot; }
;     const int c = lane & 7;
; #pragma unroll
;     for (int j = 0; j < 8; ++j) { const int n = (lane >> 3) + 8 * j; const LAS unsigned short* s_ = scr + (8 * c) * TP + n;
;         v4u o; o.x = (unsigned)s_[0 * TP] | ((unsigned)s_[1 * TP] << 16); o.y = (unsigned)s_[2 * TP] | ((unsigned)s_[3 * TP] << 16);
;         o.z = (unsigned)s_[4 * TP] | ((unsigned)s_[5 * TP] << 16); o.w = (unsigned)s_[6 * TP] | ((unsigned)s_[7 * TP] << 16);
;         *(GAS v4u*)(WT + (size_t)(dn0 + n) * K + k0 + 8 * c) = o; }
.LBB0_8:
	s_lshl_b64 s[8:9], s[8:9], 23
	v_readlane_b32 s0, v254, 17
	s_add_u32 s0, s0, s8
	v_readlane_b32 s7, v254, 18
	s_addc_u32 s7, s7, s9
	s_ashr_i32 s11, s10, 31
	s_lshl_b64 s[8:9], s[10:11], 1
	s_add_u32 s8, s0, s8
	s_addc_u32 s9, s7, s9
	v_mov_b32_e32 v5, v3
	v_lshl_add_u64 v[6:7], s[8:9], 0, v[4:5]
	ds_read_u16 v5, v9
	ds_read_u16 v21, v9 offset:16
	ds_read_u16 v28, v9 offset:32
	ds_read_u16 v29, v9 offset:48
	ds_read_u16 v30, v9 offset:64
	ds_read_u16 v31, v9 offset:80
	ds_read_u16 v32, v9 offset:96
	ds_read_u16 v33, v9 offset:112
	ds_read_u16 v22, v9 offset:136
	ds_read_u16 v34, v9 offset:152
	ds_read_u16 v35, v9 offset:168
	ds_read_u16 v36, v9 offset:184
	ds_read_u16 v37, v9 offset:200
	ds_read_u16 v38, v9 offset:216
	ds_read_u16 v39, v9 offset:232
	ds_read_u16 v40, v9 offset:248
	s_waitcnt lgkmcnt(7)
	v_lshl_or_b32 v22, v22, 16, v5
	ds_read_u16 v5, v9 offset:272
	ds_read_u16 v41, v9 offset:288
	ds_read_u16 v42, v9 offset:304
	ds_read_u16 v43, v9 offset:320
	ds_read_u16 v44, v9 offset:336
	ds_read_u16 v45, v9 offset:352
	ds_read_u16 v46, v9 offset:368
	ds_read_u16 v47, v9 offset:384
	ds_read_u16 v23, v9 offset:408
	ds_read_u16 v48, v9 offset:424
	ds_read_u16 v49, v9 offset:440
	ds_read_u16 v50, v9 offset:456
	ds_read_u16 v51, v9 offset:472
	ds_read_u16 v52, v9 offset:488
	ds_read_u16 v53, v9 offset:504
	ds_read_u16 v54, v9 offset:520
	v_add_u32_e32 v26, s6, v8
	s_waitcnt lgkmcnt(7)
	v_lshl_or_b32 v23, v23, 16, v5
	ds_read_u16 v5, v9 offset:544
	ds_read_u16 v55, v9 offset:560
	ds_read_u16 v56, v9 offset:576
	ds_read_u16 v57, v9 offset:592
	ds_read_u16 v58, v9 offset:608
	ds_read_u16 v59, v9 offset:624
	ds_read_u16 v60, v9 offset:640
	ds_read_u16 v61, v9 offset:656
	ds_read_u16 v24, v9 offset:680
	ds_read_u16 v62, v9 offset:696
	ds_read_u16 v63, v9 offset:712
	ds_read_u16 v64, v9 offset:728
	ds_read_u16 v65, v9 offset:744
	ds_read_u16 v66, v9 offset:760
	ds_read_u16 v67, v9 offset:776
	ds_read_u16 v68, v9 offset:792
	v_ashrrev_i32_e32 v27, 31, v26
	s_waitcnt lgkmcnt(7)
	v_lshl_or_b32 v24, v24, 16, v5
	ds_read_u16 v5, v9 offset:816
	ds_read_u16 v69, v9 offset:832
	ds_read_u16 v70, v9 offset:848
	ds_read_u16 v71, v9 offset:864
	ds_read_u16 v72, v9 offset:880
	ds_read_u16 v73, v9 offset:896
	ds_read_u16 v74, v9 offset:912
	ds_read_u16 v75, v9 offset:928
	ds_read_u16 v25, v9 offset:952
	ds_read_u16 v76, v9 offset:968
	ds_read_u16 v77, v9 offset:984
	ds_read_u16 v78, v9 offset:1000
	ds_read_u16 v79, v9 offset:1016
	ds_read_u16 v80, v9 offset:1032
	ds_read_u16 v81, v9 offset:1048
	ds_read_u16 v82, v9 offset:1064
	v_lshlrev_b64 v[26:27], 11, v[26:27]
	s_waitcnt lgkmcnt(7)
	v_lshl_or_b32 v25, v25, 16, v5
	v_lshl_add_u64 v[26:27], v[6:7], 0, v[26:27]
	global_store_dwordx4 v[26:27], v[22:25], off sc1
	v_add_u32_e32 v26, s6, v10
	v_ashrrev_i32_e32 v27, 31, v26
	v_lshlrev_b64 v[26:27], 11, v[26:27]
	v_lshl_or_b32 v22, v34, 16, v21
	v_lshl_or_b32 v23, v48, 16, v41
	v_lshl_or_b32 v24, v62, 16, v55
	s_waitcnt lgkmcnt(6)
	v_lshl_or_b32 v25, v76, 16, v69
	v_lshl_add_u64 v[26:27], v[6:7], 0, v[26:27]
	global_store_dwordx4 v[26:27], v[22:25], off sc1
	v_add_u32_e32 v26, s6, v11
	v_ashrrev_i32_e32 v27, 31, v26
	v_lshlrev_b64 v[26:27], 11, v[26:27]
	v_lshl_or_b32 v22, v35, 16, v28
	v_lshl_or_b32 v23, v49, 16, v42
	v_lshl_or_b32 v24, v63, 16, v56
	s_waitcnt lgkmcnt(5)
	v_lshl_or_b32 v25, v77, 16, v70
	v_lshl_add_u64 v[26:27], v[6:7], 0, v[26:27]
	global_store_dwordx4 v[26:27], v[22:25], off sc1
	v_add_u32_e32 v26, s6, v12
	v_ashrrev_i32_e32 v27, 31, v26
	v_lshlrev_b64 v[26:27], 11, v[26:27]
	v_lshl_or_b32 v22, v36, 16, v29
	v_lshl_or_b32 v23, v50, 16, v43
	v_lshl_or_b32 v24, v64, 16, v57
	s_waitcnt lgkmcnt(4)
	v_lshl_or_b32 v25, v78, 16, v71
	v_lshl_add_u64 v[26:27], v[6:7], 0, v[26:27]
	global_store_dwordx4 v[26:27], v[22:25], off sc1
	v_add_u32_e32 v26, s6, v13
	v_ashrrev_i32_e32 v27, 31, v26
	v_lshlrev_b64 v[26:27], 11, v[26:27]
	v_lshl_or_b32 v22, v37, 16, v30
	v_lshl_or_b32 v23, v51, 16, v44
	v_lshl_or_b32 v24, v65, 16, v58
	s_waitcnt lgkmcnt(3)
	v_lshl_or_b32 v25, v79, 16, v72
	v_lshl_add_u64 v[26:27], v[6:7], 0, v[26:27]
	global_store_dwordx4 v[26:27], v[22:25], off sc1
	v_add_u32_e32 v26, s6, v14
	v_ashrrev_i32_e32 v27, 31, v26
	v_lshlrev_b64 v[26:27], 11, v[26:27]
	v_lshl_or_b32 v22, v38, 16, v31
	v_lshl_or_b32 v23, v52, 16, v45
	v_lshl_or_b32 v24, v66, 16, v59
	s_waitcnt lgkmcnt(2)
	v_lshl_or_b32 v25, v80, 16, v73
	v_lshl_add_u64 v[26:27], v[6:7], 0, v[26:27]
	global_store_dwordx4 v[26:27], v[22:25], off sc1
	v_add_u32_e32 v26, s6, v15
	v_ashrrev_i32_e32 v27, 31, v26
	v_lshlrev_b64 v[26:27], 11, v[26:27]
	v_lshl_or_b32 v22, v39, 16, v32
	v_lshl_or_b32 v23, v53, 16, v46
	v_lshl_or_b32 v24, v67, 16, v60
	s_waitcnt lgkmcnt(1)
	v_lshl_or_b32 v25, v81, 16, v74
	v_lshl_add_u64 v[26:27], v[6:7], 0, v[26:27]
	global_store_dwordx4 v[26:27], v[22:25], off sc1
	v_add_u32_e32 v26, s6, v16
	v_ashrrev_i32_e32 v27, 31, v26
	v_lshlrev_b64 v[26:27], 11, v[26:27]
	v_lshl_or_b32 v22, v40, 16, v33
	v_lshl_or_b32 v23, v54, 16, v47
	v_lshl_or_b32 v24, v68, 16, v61
	s_waitcnt lgkmcnt(0)
	v_lshl_or_b32 v25, v82, 16, v75
	v_lshl_add_u64 v[6:7], v[6:7], 0, v[26:27]
	global_store_dwordx4 v[6:7], v[22:25], off sc1
	s_waitcnt lgkmcnt(0)

; #define GAS __attribute__((address_space(1)))
; #define LAS __attribute__((address_space(3)))
; __device__ __forceinline__ unsigned pk2(float lo, float hi) { return f2bf(lo) | (f2bf(hi) << 16); }
; __device__ __forceinline__ void p0_transpose_item(const float* W, int K, int N, bf16* WT, int conv, LAS float* scrf, int item, int lane, const float* gk) {
;     ...
;     const int nblk = N / 64, kb = item / nblk, nb = item % nblk, k0 = 64 * kb, n0 = 64 * nb;
;     const int lr = lane >> 4, lc = (lane & 15) * 4;
;     f32x4 v[16];
; #pragma unroll
;     for (int i = 0; i < 16; ++i) v[i] = *(const GAS f32x4*)(W + (size_t)(k0 + 4 * i + lr) * N + n0 + lc);
; #pragma unroll
;     for (int i = 0; i < 16; ++i) { const float g_ = gk ? gk[k0 + 4 * i + lr] : 1.0f; const f32x4 y = v[i] * g_;
;         *(LAS unsigned long long*)(scr + (4 * i + lr) * TP + lc) = (unsigned long long)pk2(y.x, y.y) | ((unsigned long long)pk2(y.z, y.w) << 32); }
; __global__ void __launch_bounds__(NWAVES * 64, 2) trunk_fwd(Args args) {
;     ...
;             else { const int it2 = it - DEPTH * I_IN; const int l = it2 / I_OUT, r = it2 % I_OUT; p0_transpose_item(w_out + (size_t)l * D * D, D, D, Wout_t + (size_t)l * D * D, 0, scr, r, lane, nullptr); }
.LBB0_10:
	s_cmpk_gt_i32 s36, 0xfff
	s_mov_b64 s[6:7], -1
	s_cbranch_scc0 .LBB0_12
	s_add_i32 s0, s36, 0xfffff000
	s_lshr_b32 s0, s0, 8
	v_readlane_b32 s76, v254, 1
	s_lshl_b64 s[6:7], s[0:1], 22
	v_readlane_b32 s82, v254, 7
	v_readlane_b32 s83, v254, 8
	s_add_u32 s9, s82, s6
	s_addc_u32 s11, s83, s7
	s_lshl_b64 s[6:7], s[0:1], 21
	v_readlane_b32 s0, v254, 19
	s_add_u32 s6, s0, s6
	v_readlane_b32 s0, v254, 20
	s_addc_u32 s7, s0, s7
	s_and_b32 s0, s14, 0x3c0
	s_and_b32 s8, s12, 0x3c0
	s_lshl_b32 s10, s0, 2
	s_add_u32 s10, s9, s10
	v_or_b32_e32 v5, s8, v1
	s_addc_u32 s11, s11, 0
	v_lshl_add_u64 v[6:7], s[10:11], 0, v[2:3]
	v_lshlrev_b32_e32 v22, 12, v5
	v_mov_b32_e32 v23, v3
	v_lshl_add_u64 v[6:7], v[6:7], 0, v[22:23]
	global_load_dwordx4 v[22:25], v[6:7], off
	v_add_co_u32_e32 v26, vcc, s16, v6
	s_lshl_b32 s8, s8, 1
	s_nop 0
	v_addc_co_u32_e32 v27, vcc, 0, v7, vcc
	global_load_dwordx4 v[26:29], v[26:27], off
	v_add_co_u32_e32 v30, vcc, s17, v6
	s_add_u32 s6, s6, s8
	s_nop 0
	v_addc_co_u32_e32 v31, vcc, 0, v7, vcc
	v_add_co_u32_e32 v34, vcc, s18, v6
	s_addc_u32 s7, s7, 0
	s_nop 0
	v_addc_co_u32_e32 v35, vcc, 0, v7, vcc
	global_load_dwordx4 v[30:33], v[30:31], off
	s_nop 0
	global_load_dwordx4 v[34:37], v[34:35], off
	v_add_co_u32_e32 v38, vcc, s19, v6
	v_readlane_b32 s77, v254, 2
	s_nop 0
	v_addc_co_u32_e32 v39, vcc, 0, v7, vcc
	v_add_co_u32_e32 v42, vcc, s20, v6
	v_readlane_b32 s78, v254, 3
	s_nop 0
	v_addc_co_u32_e32 v43, vcc, 0, v7, vcc
	global_load_dwordx4 v[38:41], v[38:39], off
	s_nop 0
	global_load_dwordx4 v[42:45], v[42:43], off
	v_add_co_u32_e32 v46, vcc, s21, v6
	v_readlane_b32 s79, v254, 4
	s_nop 0
	v_addc_co_u32_e32 v47, vcc, 0, v7, vcc
	v_add_co_u32_e32 v50, vcc, s23, v6
	v_readlane_b32 s80, v254, 5
	s_nop 0
	v_addc_co_u32_e32 v51, vcc, 0, v7, vcc
	global_load_dwordx4 v[46:49], v[46:47], off
	s_nop 0
	global_load_dwordx4 v[50:53], v[50:51], off
	v_add_co_u32_e32 v54, vcc, s24, v6
	v_readlane_b32 s81, v254, 6
	s_nop 0
	v_addc_co_u32_e32 v55, vcc, 0, v7, vcc
	v_add_co_u32_e32 v58, vcc, s25, v6
	v_readlane_b32 s84, v254, 9
	s_nop 0
	v_addc_co_u32_e32 v59, vcc, 0, v7, vcc
	global_load_dwordx4 v[54:57], v[54:55], off
	s_nop 0
	global_load_dwordx4 v[58:61], v[58:59], off
	v_add_co_u32_e32 v62, vcc, s26, v6
	v_readlane_b32 s85, v254, 10
	s_nop 0
	v_addc_co_u32_e32 v63, vcc, 0, v7, vcc
	v_add_co_u32_e32 v66, vcc, s27, v6
	v_readlane_b32 s86, v254, 11
	s_nop 0
	v_addc_co_u32_e32 v67, vcc, 0, v7, vcc
	global_load_dwordx4 v[62:65], v[62:63], off
	s_nop 0
	global_load_dwordx4 v[66:69], v[66:67], off
	v_add_co_u32_e32 v70, vcc, s28, v6
	v_readlane_b32 s87, v254, 12
	s_nop 0
	v_addc_co_u32_e32 v71, vcc, 0, v7, vcc
	v_add_co_u32_e32 v74, vcc, s29, v6
	v_readlane_b32 s88, v254, 13
	s_nop 0
	v_addc_co_u32_e32 v75, vcc, 0, v7, vcc
	global_load_dwordx4 v[70:73], v[70:71], off
	s_nop 0
	global_load_dwordx4 v[74:77], v[74:75], off
	v_add_co_u32_e32 v78, vcc, s30, v6
	v_readlane_b32 s89, v254, 14
	s_nop 0
	v_addc_co_u32_e32 v79, vcc, 0, v7, vcc
	v_add_co_u32_e32 v6, vcc, s31, v6
	s_waitcnt vmcnt(13)
	v_bfe_u32 v5, v22, 16, 1
	v_addc_co_u32_e32 v7, vcc, 0, v7, vcc
	global_load_dwordx4 v[78:81], v[78:79], off
	s_nop 0
	global_load_dwordx4 v[82:85], v[6:7], off
	v_add3_u32 v5, v22, v5, s34
	v_bfe_u32 v6, v23, 16, 1
	v_lshrrev_b32_e32 v5, 16, v5
	v_add3_u32 v6, v23, v6, s34
	v_and_or_b32 v6, v6, s35, v5
	v_bfe_u32 v5, v24, 16, 1
	v_add3_u32 v5, v24, v5, s34
	v_bfe_u32 v7, v25, 16, 1
	v_lshrrev_b32_e32 v5, 16, v5
	v_add3_u32 v7, v25, v7, s34
	v_and_or_b32 v7, v7, s35, v5
	s_waitcnt vmcnt(14)
	v_bfe_u32 v5, v26, 16, 1
	v_add3_u32 v5, v26, v5, s34
	v_bfe_u32 v21, v27, 16, 1
	v_lshrrev_b32_e32 v5, 16, v5
	v_add3_u32 v21, v27, v21, s34
	v_and_or_b32 v22, v21, s35, v5
	v_bfe_u32 v5, v28, 16, 1
	v_add3_u32 v5, v28, v5, s34
	v_bfe_u32 v21, v29, 16, 1
	v_lshrrev_b32_e32 v5, 16, v5
	v_add3_u32 v21, v29, v21, s34
	v_and_or_b32 v23, v21, s35, v5
	s_waitcnt vmcnt(13)
	v_bfe_u32 v5, v30, 16, 1
	ds_write2_b64 v17, v[6:7], v[22:23] offset1:68
	v_add3_u32 v5, v30, v5, s34
	v_bfe_u32 v6, v31, 16, 1
	v_lshrrev_b32_e32 v5, 16, v5
	v_add3_u32 v6, v31, v6, s34
	v_and_or_b32 v6, v6, s35, v5
	v_bfe_u32 v5, v32, 16, 1
	v_add3_u32 v5, v32, v5, s34
	v_bfe_u32 v7, v33, 16, 1
	v_lshrrev_b32_e32 v5, 16, v5
	v_add3_u32 v7, v33, v7, s34
	v_and_or_b32 v7, v7, s35, v5
	s_waitcnt vmcnt(12)
	v_bfe_u32 v5, v34, 16, 1
	v_add3_u32 v5, v34, v5, s34
	v_bfe_u32 v21, v35, 16, 1
	v_lshrrev_b32_e32 v5, 16, v5
	v_add3_u32 v21, v35, v21, s34
	v_and_or_b32 v22, v21, s35, v5
	v_bfe_u32 v5, v36, 16, 1
	v_add3_u32 v5, v36, v5, s34
	v_bfe_u32 v21, v37, 16, 1
	v_lshrrev_b32_e32 v5, 16, v5
	v_add3_u32 v21, v37, v21, s34
	v_and_or_b32 v23, v21, s35, v5
	s_waitcnt vmcnt(11)
	v_bfe_u32 v5, v38, 16, 1
	ds_write2_b64 v17, v[6:7], v[22:23] offset0:136 offset1:204
	v_add3_u32 v5, v38, v5, s34
	v_bfe_u32 v6, v39, 16, 1
	v_lshrrev_b32_e32 v5, 16, v5
	v_add3_u32 v6, v39, v6, s34
	v_and_or_b32 v6, v6, s35, v5
	v_bfe_u32 v5, v40, 16, 1
	v_add3_u32 v5, v40, v5, s34
	v_bfe_u32 v7, v41, 16, 1
	v_lshrrev_b32_e32 v5, 16, v5
	v_add3_u32 v7, v41, v7, s34
	v_and_or_b32 v7, v7, s35, v5
	s_waitcnt vmcnt(10)
	v_bfe_u32 v5, v42, 16, 1
	v_add3_u32 v5, v42, v5, s34
	v_bfe_u32 v21, v43, 16, 1
	v_lshrrev_b32_e32 v5, 16, v5
	v_add3_u32 v21, v43, v21, s34
	v_and_or_b32 v22, v21, s35, v5
	v_bfe_u32 v5, v44, 16, 1
	v_add3_u32 v5, v44, v5, s34
	v_bfe_u32 v21, v45, 16, 1
	v_lshrrev_b32_e32 v5, 16, v5
	v_add3_u32 v21, v45, v21, s34
	v_and_or_b32 v23, v21, s35, v5
	s_waitcnt vmcnt(9)
; #define LAS __attribute__((address_space(3)))
; __device__ __forceinline__ unsigned pk2(float lo, float hi) { return f2bf(lo) | (f2bf(hi) << 16); }
; __device__ __forceinline__ void p0_transpose_item(const float* W, int K, int N, bf16* WT, int conv, LAS float* scrf, int item, int lane, const float* gk) {
;     ...
;     for (int i = 0; i < 16; ++i) { const float g_ = gk ? gk[k0 + 4 * i + lr] : 1.0f; const f32x4 y = v[i] * g_;
;         *(LAS unsigned long long*)(scr + (4 * i + lr) * TP + lc) = (unsigned long long)pk2(y.x, y.y) | ((unsigned long long)pk2(y.z, y.w) << 32); }
;     ...
;     for (int j = 0; j < 8; ++j) { const int n = (lane >> 3) + 8 * j; const LAS unsigned short* s_ = scr + (8 * c) * TP + n;
;         v4u o; o.x = (unsigned)s_[0 * TP] | ((unsigned)s_[1 * TP] << 16); o.y = (unsigned)s_[2 * TP] | ((unsigned)s_[3 * TP] << 16);
;         o.z = (unsigned)s_[4 * TP] | ((unsigned)s_[5 * TP] << 16); o.w = (unsigned)s_[6 * TP] | ((unsigned)s_[7 * TP] << 16);
	v_bfe_u32 v5, v46, 16, 1
	ds_write2_b64 v18, v[6:7], v[22:23] offset0:16 offset1:84
	v_add3_u32 v5, v46, v5, s34
	v_bfe_u32 v6, v47, 16, 1
	v_lshrrev_b32_e32 v5, 16, v5
	v_add3_u32 v6, v47, v6, s34
	v_and_or_b32 v6, v6, s35, v5
	v_bfe_u32 v5, v48, 16, 1
	v_add3_u32 v5, v48, v5, s34
	v_bfe_u32 v7, v49, 16, 1
	v_lshrrev_b32_e32 v5, 16, v5
	v_add3_u32 v7, v49, v7, s34
	v_and_or_b32 v7, v7, s35, v5
	s_waitcnt vmcnt(8)
	v_bfe_u32 v5, v50, 16, 1
	v_add3_u32 v5, v50, v5, s34
	v_bfe_u32 v21, v51, 16, 1
	v_lshrrev_b32_e32 v5, 16, v5
	v_add3_u32 v21, v51, v21, s34
	v_and_or_b32 v22, v21, s35, v5
	v_bfe_u32 v5, v52, 16, 1
	v_add3_u32 v5, v52, v5, s34
	v_bfe_u32 v21, v53, 16, 1
	v_lshrrev_b32_e32 v5, 16, v5
	v_add3_u32 v21, v53, v21, s34
	v_and_or_b32 v23, v21, s35, v5
	s_waitcnt vmcnt(7)
	v_bfe_u32 v5, v54, 16, 1
	ds_write2_b64 v18, v[6:7], v[22:23] offset0:152 offset1:220
	v_add3_u32 v5, v54, v5, s34
	v_bfe_u32 v6, v55, 16, 1
	v_lshrrev_b32_e32 v5, 16, v5
	v_add3_u32 v6, v55, v6, s34
	v_and_or_b32 v6, v6, s35, v5
	v_bfe_u32 v5, v56, 16, 1
	v_add3_u32 v5, v56, v5, s34
	v_bfe_u32 v7, v57, 16, 1
	v_lshrrev_b32_e32 v5, 16, v5
	v_add3_u32 v7, v57, v7, s34
	v_and_or_b32 v7, v7, s35, v5
	s_waitcnt vmcnt(6)
	v_bfe_u32 v5, v58, 16, 1
	v_add3_u32 v5, v58, v5, s34
	v_bfe_u32 v21, v59, 16, 1
	v_lshrrev_b32_e32 v5, 16, v5
	v_add3_u32 v21, v59, v21, s34
	v_and_or_b32 v22, v21, s35, v5
	v_bfe_u32 v5, v60, 16, 1
	v_add3_u32 v5, v60, v5, s34
	v_bfe_u32 v21, v61, 16, 1
	v_lshrrev_b32_e32 v5, 16, v5
	v_add3_u32 v21, v61, v21, s34
	v_and_or_b32 v23, v21, s35, v5
	s_waitcnt vmcnt(5)
	v_bfe_u32 v5, v62, 16, 1
	ds_write2_b64 v19, v[6:7], v[22:23] offset0:32 offset1:100
	v_add3_u32 v5, v62, v5, s34
	v_bfe_u32 v6, v63, 16, 1
	v_lshrrev_b32_e32 v5, 16, v5
	v_add3_u32 v6, v63, v6, s34
	v_and_or_b32 v6, v6, s35, v5
	v_bfe_u32 v5, v64, 16, 1
	v_add3_u32 v5, v64, v5, s34
	v_bfe_u32 v7, v65, 16, 1
	v_lshrrev_b32_e32 v5, 16, v5
	v_add3_u32 v7, v65, v7, s34
	v_and_or_b32 v7, v7, s35, v5
	s_waitcnt vmcnt(4)
	v_bfe_u32 v5, v66, 16, 1
	v_add3_u32 v5, v66, v5, s34
	v_bfe_u32 v21, v67, 16, 1
	v_lshrrev_b32_e32 v5, 16, v5
	v_add3_u32 v21, v67, v21, s34
	v_and_or_b32 v22, v21, s35, v5
	v_bfe_u32 v5, v68, 16, 1
	v_add3_u32 v5, v68, v5, s34
	v_bfe_u32 v21, v69, 16, 1
	v_lshrrev_b32_e32 v5, 16, v5
	v_add3_u32 v21, v69, v21, s34
	v_and_or_b32 v23, v21, s35, v5
	s_waitcnt vmcnt(3)
	v_bfe_u32 v5, v70, 16, 1
	ds_write2_b64 v19, v[6:7], v[22:23] offset0:168 offset1:236
	v_add3_u32 v5, v70, v5, s34
	v_bfe_u32 v6, v71, 16, 1
	v_lshrrev_b32_e32 v5, 16, v5
	v_add3_u32 v6, v71, v6, s34
	v_and_or_b32 v6, v6, s35, v5
	v_bfe_u32 v5, v72, 16, 1
	v_add3_u32 v5, v72, v5, s34
	v_bfe_u32 v7, v73, 16, 1
	v_lshrrev_b32_e32 v5, 16, v5
	v_add3_u32 v7, v73, v7, s34
	v_and_or_b32 v7, v7, s35, v5
	s_waitcnt vmcnt(2)
	v_bfe_u32 v5, v74, 16, 1
	v_add3_u32 v5, v74, v5, s34
	v_bfe_u32 v21, v75, 16, 1
	v_lshrrev_b32_e32 v5, 16, v5
	v_add3_u32 v21, v75, v21, s34
	v_and_or_b32 v22, v21, s35, v5
	v_bfe_u32 v5, v76, 16, 1
	v_add3_u32 v5, v76, v5, s34
	v_bfe_u32 v21, v77, 16, 1
	v_lshrrev_b32_e32 v5, 16, v5
	v_add3_u32 v21, v77, v21, s34
	v_and_or_b32 v23, v21, s35, v5
	s_waitcnt vmcnt(1)
	v_bfe_u32 v5, v78, 16, 1
	ds_write2_b64 v20, v[6:7], v[22:23] offset0:48 offset1:116
	v_add3_u32 v5, v78, v5, s34
	v_bfe_u32 v6, v79, 16, 1
	v_lshrrev_b32_e32 v5, 16, v5
	v_add3_u32 v6, v79, v6, s34
	v_and_or_b32 v6, v6, s35, v5
	v_bfe_u32 v5, v80, 16, 1
	v_add3_u32 v5, v80, v5, s34
	v_bfe_u32 v7, v81, 16, 1
	v_lshrrev_b32_e32 v5, 16, v5
	v_add3_u32 v7, v81, v7, s34
	v_and_or_b32 v7, v7, s35, v5
	s_waitcnt vmcnt(0)
	v_bfe_u32 v5, v82, 16, 1
	v_add3_u32 v5, v82, v5, s34
	v_bfe_u32 v21, v83, 16, 1
	v_lshrrev_b32_e32 v5, 16, v5
	v_add3_u32 v21, v83, v21, s34
	v_and_or_b32 v22, v21, s35, v5
	v_bfe_u32 v5, v84, 16, 1
	v_add3_u32 v5, v84, v5, s34
	v_bfe_u32 v21, v85, 16, 1
	v_lshrrev_b32_e32 v5, 16, v5
	v_add3_u32 v21, v85, v21, s34
	v_and_or_b32 v23, v21, s35, v5
	ds_write2_b64 v20, v[6:7], v[22:23] offset0:184 offset1:252
	s_waitcnt lgkmcnt(0)
	v_mov_b32_e32 v5, v3
	v_lshl_add_u64 v[6:7], s[6:7], 0, v[4:5]
	ds_read_u16 v5, v9
	ds_read_u16 v21, v9 offset:16
	ds_read_u16 v28, v9 offset:32
	ds_read_u16 v29, v9 offset:48
	ds_read_u16 v30, v9 offset:64
	ds_read_u16 v31, v9 offset:80
	ds_read_u16 v32, v9 offset:96
	ds_read_u16 v33, v9 offset:112
	ds_read_u16 v22, v9 offset:136
	ds_read_u16 v34, v9 offset:152
	ds_read_u16 v35, v9 offset:168
	ds_read_u16 v36, v9 offset:184
	ds_read_u16 v37, v9 offset:200
	ds_read_u16 v38, v9 offset:216
	ds_read_u16 v39, v9 offset:232
	ds_read_u16 v40, v9 offset:248
	s_waitcnt lgkmcnt(7)
; #define GAS __attribute__((address_space(1)))
; #define LAS __attribute__((address_space(3)))
; __device__ __forceinline__ void p0_transpose_item(const float* W, int K, int N, bf16* WT, int conv, LAS float* scrf, int item, int lane, const float* gk) {
;     ...
;     for (int j = 0; j < 8; ++j) { const int n = (lane >> 3) + 8 * j; const LAS unsigned short* s_ = scr + (8 * c) * TP + n;
;         v4u o; o.x = (unsigned)s_[0 * TP] | ((unsigned)s_[1 * TP] << 16); o.y = (unsigned)s_[2 * TP] | ((unsigned)s_[3 * TP] << 16);
;         o.z = (unsigned)s_[4 * TP] | ((unsigned)s_[5 * TP] << 16); o.w = (unsigned)s_[6 * TP] | ((unsigned)s_[7 * TP] << 16);
;         *(GAS v4u*)(WT + (size_t)(dn0 + n) * K + k0 + 8 * c) = o; }
	v_lshl_or_b32 v22, v22, 16, v5
	ds_read_u16 v5, v9 offset:272
	ds_read_u16 v41, v9 offset:288
	ds_read_u16 v42, v9 offset:304
	ds_read_u16 v43, v9 offset:320
	ds_read_u16 v44, v9 offset:336
	ds_read_u16 v45, v9 offset:352
	ds_read_u16 v46, v9 offset:368
	ds_read_u16 v47, v9 offset:384
	ds_read_u16 v23, v9 offset:408
	ds_read_u16 v48, v9 offset:424
	ds_read_u16 v49, v9 offset:440
	ds_read_u16 v50, v9 offset:456
	ds_read_u16 v51, v9 offset:472
	ds_read_u16 v52, v9 offset:488
	ds_read_u16 v53, v9 offset:504
	ds_read_u16 v54, v9 offset:520
	s_waitcnt lgkmcnt(7)
	v_lshl_or_b32 v23, v23, 16, v5
	ds_read_u16 v5, v9 offset:544
	ds_read_u16 v55, v9 offset:560
	ds_read_u16 v56, v9 offset:576
	ds_read_u16 v57, v9 offset:592
	ds_read_u16 v58, v9 offset:608
	ds_read_u16 v59, v9 offset:624
	ds_read_u16 v60, v9 offset:640
	ds_read_u16 v61, v9 offset:656
	ds_read_u16 v24, v9 offset:680
	ds_read_u16 v62, v9 offset:696
	ds_read_u16 v63, v9 offset:712
	ds_read_u16 v64, v9 offset:728
	ds_read_u16 v65, v9 offset:744
	ds_read_u16 v66, v9 offset:760
	ds_read_u16 v67, v9 offset:776
	ds_read_u16 v68, v9 offset:792
	s_waitcnt lgkmcnt(7)
	v_lshl_or_b32 v24, v24, 16, v5
	ds_read_u16 v5, v9 offset:816
	ds_read_u16 v69, v9 offset:832
	ds_read_u16 v70, v9 offset:848
	ds_read_u16 v71, v9 offset:864
	ds_read_u16 v72, v9 offset:880
	ds_read_u16 v73, v9 offset:896
	ds_read_u16 v74, v9 offset:912
	ds_read_u16 v75, v9 offset:928
	ds_read_u16 v25, v9 offset:952
	ds_read_u16 v76, v9 offset:968
	ds_read_u16 v77, v9 offset:984
	ds_read_u16 v78, v9 offset:1000
	ds_read_u16 v79, v9 offset:1016
	ds_read_u16 v80, v9 offset:1032
	ds_read_u16 v81, v9 offset:1048
	ds_read_u16 v82, v9 offset:1064
	s_waitcnt lgkmcnt(7)
	v_lshl_or_b32 v25, v25, 16, v5
	v_or_b32_e32 v5, s0, v8
	v_lshlrev_b32_e32 v26, 11, v5
	v_mov_b32_e32 v27, v3
	v_lshl_add_u64 v[26:27], v[6:7], 0, v[26:27]
	v_or_b32_e32 v5, s0, v10
	global_store_dwordx4 v[26:27], v[22:25], off sc1
	v_lshlrev_b32_e32 v26, 11, v5
	v_mov_b32_e32 v27, v3
	v_lshl_or_b32 v22, v34, 16, v21
	v_lshl_or_b32 v23, v48, 16, v41
	v_lshl_or_b32 v24, v62, 16, v55
	s_waitcnt lgkmcnt(6)
	v_lshl_or_b32 v25, v76, 16, v69
	v_lshl_add_u64 v[26:27], v[6:7], 0, v[26:27]
	v_or_b32_e32 v5, s0, v11
	global_store_dwordx4 v[26:27], v[22:25], off sc1
	v_lshlrev_b32_e32 v26, 11, v5
	v_mov_b32_e32 v27, v3
	v_lshl_or_b32 v22, v35, 16, v28
	v_lshl_or_b32 v23, v49, 16, v42
	v_lshl_or_b32 v24, v63, 16, v56
	s_waitcnt lgkmcnt(5)
	v_lshl_or_b32 v25, v77, 16, v70
	v_lshl_add_u64 v[26:27], v[6:7], 0, v[26:27]
	v_or_b32_e32 v5, s0, v12
	global_store_dwordx4 v[26:27], v[22:25], off sc1
	v_lshlrev_b32_e32 v26, 11, v5
	v_mov_b32_e32 v27, v3
	v_lshl_or_b32 v22, v36, 16, v29
	v_lshl_or_b32 v23, v50, 16, v43
	v_lshl_or_b32 v24, v64, 16, v57
	s_waitcnt lgkmcnt(4)
	v_lshl_or_b32 v25, v78, 16, v71
	v_lshl_add_u64 v[26:27], v[6:7], 0, v[26:27]
	v_or_b32_e32 v5, s0, v13
	global_store_dwordx4 v[26:27], v[22:25], off sc1
	v_lshlrev_b32_e32 v26, 11, v5
	v_mov_b32_e32 v27, v3
	v_lshl_or_b32 v22, v37, 16, v30
	v_lshl_or_b32 v23, v51, 16, v44
	v_lshl_or_b32 v24, v65, 16, v58
	s_waitcnt lgkmcnt(3)
	v_lshl_or_b32 v25, v79, 16, v72
	v_lshl_add_u64 v[26:27], v[6:7], 0, v[26:27]
	v_or_b32_e32 v5, s0, v14
	global_store_dwordx4 v[26:27], v[22:25], off sc1
	v_lshlrev_b32_e32 v26, 11, v5
	v_mov_b32_e32 v27, v3
	v_lshl_or_b32 v22, v38, 16, v31
	v_lshl_or_b32 v23, v52, 16, v45
	v_lshl_or_b32 v24, v66, 16, v59
	s_waitcnt lgkmcnt(2)
	v_lshl_or_b32 v25, v80, 16, v73
	v_lshl_add_u64 v[26:27], v[6:7], 0, v[26:27]
	v_or_b32_e32 v5, s0, v15
	global_store_dwordx4 v[26:27], v[22:25], off sc1
	v_lshlrev_b32_e32 v26, 11, v5
	v_mov_b32_e32 v27, v3
	v_lshl_or_b32 v22, v39, 16, v32
	v_lshl_or_b32 v23, v53, 16, v46
	v_lshl_or_b32 v24, v67, 16, v60
	s_waitcnt lgkmcnt(1)
	v_lshl_or_b32 v25, v81, 16, v74
	v_lshl_add_u64 v[26:27], v[6:7], 0, v[26:27]
	v_or_b32_e32 v5, s0, v16
	global_store_dwordx4 v[26:27], v[22:25], off sc1
	v_lshlrev_b32_e32 v26, 11, v5
	v_mov_b32_e32 v27, v3
	v_lshl_or_b32 v22, v40, 16, v33
	v_lshl_or_b32 v23, v54, 16, v47
	v_lshl_or_b32 v24, v68, 16, v61
	s_waitcnt lgkmcnt(0)
	v_lshl_or_b32 v25, v82, 16, v75
	v_lshl_add_u64 v[6:7], v[6:7], 0, v[26:27]
	global_store_dwordx4 v[6:7], v[22:25], off sc1
	s_waitcnt lgkmcnt(0)
	v_readlane_b32 s90, v254, 15
	v_readlane_b32 s91, v254, 16
	s_mov_b64 s[6:7], 0

; __device__ __forceinline__ unsigned cvt_pk_bf16(float lo, float hi) { unsigned r; asm volatile("v_cvt_pk_bf16_f32 %0, %1, %2" : "=v"(r) : "v"(lo), "v"(hi)); return r; }
;     __device__ __forceinline__ void operator()(const f32x4 (&acc)[2][2][4][2], const Unit& u, int wr, int wc, int fr, int fq) const {
;     ...
;             const int b = u.pm >> 5, t0 = (u.pm & 31) * 4 + wr;
;             const int inner = (4 * wc + fq) * 1024 + fr * 16;
; #pragma unroll
;             for (int bj = 0; bj < 2; ++bj) { const int h = (u.pn & 3) * 2 + bj;
; #pragma unroll
;                 for (int ai = 0; ai < 2; ++ai) { unsigned char* img = KV + ((size_t)((b * 8 + h) * 128 + t0 + 2 * ai) << 15) + inner;
; #pragma unroll
;                     for (int m = 0; m < 4; ++m) { const f32x4 v0 = acc[ai][bj][m][0], v1 = acc[ai][bj][m][1];
;                         u32x4 w; w.x = cvt_pk_bf16(v0[0], v0[1]); w.y = cvt_pk_bf16(v0[2], v0[3]); w.z = cvt_pk_bf16(v1[0], v1[1]); w.w = cvt_pk_bf16(v1[2], v1[3]);
;                         *(u32x4*)(img + m * 256) = w; } } }
.LBB0_122:
	s_andn2_b64 vcc, exec, s[92:93]
	s_cbranch_vccnz .LBB0_124
	v_lshl_add_u64 v[152:153], s[30:31], 0, v[140:141]
	v_cvt_pk_bf16_f32 v158, v126, v127
	v_cvt_pk_bf16_f32 v159, v128, v129
	v_cvt_pk_bf16_f32 v160, v122, v123
	v_cvt_pk_bf16_f32 v161, v124, v125
	global_store_dwordx4 v[152:153], v[158:161], off sc1
	s_lshl_b64 s[22:23], s[8:9], 15
	s_mov_b64 s[20:21], 0x10000
	v_cvt_pk_bf16_f32 v158, v114, v115
	v_cvt_pk_bf16_f32 v159, v116, v117
	v_cvt_pk_bf16_f32 v160, v106, v107
	v_cvt_pk_bf16_f32 v161, v108, v109
	global_store_dwordx4 v[152:153], v[158:161], off offset:256 sc1
	s_addk_i32 s8, 0x80
	s_ashr_i32 s9, s8, 31
	v_cvt_pk_bf16_f32 v158, v98, v99
	v_cvt_pk_bf16_f32 v159, v100, v101
	v_cvt_pk_bf16_f32 v160, v90, v91
	v_cvt_pk_bf16_f32 v161, v92, v93
	global_store_dwordx4 v[152:153], v[158:161], off offset:512 sc1
	s_lshl_b64 s[8:9], s[8:9], 15
	s_nop 0
	v_cvt_pk_bf16_f32 v158, v82, v83
	v_cvt_pk_bf16_f32 v159, v84, v85
	v_cvt_pk_bf16_f32 v160, v74, v75
	v_cvt_pk_bf16_f32 v161, v76, v77
	global_store_dwordx4 v[152:153], v[158:161], off offset:768 sc1
	v_lshl_add_u64 v[152:153], v[144:145], 0, s[22:23]
	v_lshl_add_u64 v[162:163], v[152:153], 0, s[20:21]
	v_add_co_u32_e32 v152, vcc, s54, v152
	v_cvt_pk_bf16_f32 v158, v62, v63
	v_cvt_pk_bf16_f32 v159, v64, v65
	v_cvt_pk_bf16_f32 v160, v58, v59
	v_cvt_pk_bf16_f32 v161, v60, v61
	s_nop 1
	v_addc_co_u32_e32 v153, vcc, 0, v153, vcc
	global_store_dwordx4 v[152:153], v[158:161], off sc1
	v_lshl_add_u64 v[152:153], v[144:145], 0, s[8:9]
	s_nop 0
	v_cvt_pk_bf16_f32 v158, v50, v51
	v_cvt_pk_bf16_f32 v159, v52, v53
	v_cvt_pk_bf16_f32 v160, v42, v43
	v_cvt_pk_bf16_f32 v161, v44, v45
	global_store_dwordx4 v[162:163], v[158:161], off offset:256 sc1
	s_nop 1
	v_cvt_pk_bf16_f32 v158, v34, v35
	v_cvt_pk_bf16_f32 v159, v36, v37
	v_cvt_pk_bf16_f32 v160, v26, v27
	v_cvt_pk_bf16_f32 v161, v28, v29
	global_store_dwordx4 v[162:163], v[158:161], off offset:512 sc1
	s_nop 1
	v_cvt_pk_bf16_f32 v158, v18, v19
	v_cvt_pk_bf16_f32 v159, v20, v21
	v_cvt_pk_bf16_f32 v160, v10, v11
	v_cvt_pk_bf16_f32 v161, v12, v13
	global_store_dwordx4 v[162:163], v[158:161], off offset:768 sc1
	v_lshl_add_u64 v[162:163], v[152:153], 0, s[20:21]
	s_nop 0
	v_cvt_pk_bf16_f32 v158, v118, v119
	v_cvt_pk_bf16_f32 v159, v120, v121
	v_cvt_pk_bf16_f32 v160, v110, v111
	v_cvt_pk_bf16_f32 v161, v112, v113
	global_store_dwordx4 v[152:153], v[158:161], off sc1
	s_nop 1
	v_cvt_pk_bf16_f32 v158, v102, v103
	v_cvt_pk_bf16_f32 v159, v104, v105
	v_cvt_pk_bf16_f32 v160, v94, v95
	v_cvt_pk_bf16_f32 v161, v96, v97
	global_store_dwordx4 v[152:153], v[158:161], off offset:256 sc1
	s_nop 1
	v_cvt_pk_bf16_f32 v158, v86, v87
	v_cvt_pk_bf16_f32 v159, v88, v89
	v_cvt_pk_bf16_f32 v160, v78, v79
	v_cvt_pk_bf16_f32 v161, v80, v81
	global_store_dwordx4 v[152:153], v[158:161], off offset:512 sc1
	s_nop 1
	v_cvt_pk_bf16_f32 v158, v70, v71
	v_cvt_pk_bf16_f32 v159, v72, v73
	v_cvt_pk_bf16_f32 v160, v66, v67
	v_cvt_pk_bf16_f32 v161, v68, v69
	global_store_dwordx4 v[152:153], v[158:161], off offset:768 sc1
	v_add_co_u32_e32 v152, vcc, s54, v152
	s_nop 0
	v_cvt_pk_bf16_f32 v158, v54, v55
	v_cvt_pk_bf16_f32 v159, v56, v57
	v_cvt_pk_bf16_f32 v160, v46, v47
	v_cvt_pk_bf16_f32 v161, v48, v49
	s_nop 0
	v_addc_co_u32_e32 v153, vcc, 0, v153, vcc
	global_store_dwordx4 v[152:153], v[158:161], off sc1
	s_nop 1
	v_cvt_pk_bf16_f32 v158, v38, v39
	v_cvt_pk_bf16_f32 v159, v40, v41
	v_cvt_pk_bf16_f32 v160, v30, v31
	v_cvt_pk_bf16_f32 v161, v32, v33
	global_store_dwordx4 v[162:163], v[158:161], off offset:256 sc1
	s_nop 1
	v_cvt_pk_bf16_f32 v158, v22, v23
	v_cvt_pk_bf16_f32 v159, v24, v25
	v_cvt_pk_bf16_f32 v160, v14, v15
	v_cvt_pk_bf16_f32 v161, v16, v17
	global_store_dwordx4 v[162:163], v[158:161], off offset:512 sc1
	s_nop 1
	v_cvt_pk_bf16_f32 v158, v6, v7
	v_cvt_pk_bf16_f32 v159, v8, v9
	v_cvt_pk_bf16_f32 v160, v2, v3
	v_cvt_pk_bf16_f32 v161, v4, v5
	global_store_dwordx4 v[162:163], v[158:161], off offset:768 sc1

; __device__ __forceinline__ unsigned cvt_pk_bf16(float lo, float hi) { unsigned r; asm volatile("v_cvt_pk_bf16_f32 %0, %1, %2" : "=v"(r) : "v"(lo), "v"(hi)); return r; }
;     __device__ __forceinline__ void operator()(const f32x4 (&acc)[2][2][4][2], const Unit& u, int wr, int wc, int fr, int fq) const {
;         const int part = u.pn >> 2;
;         if (part == 0 || part == 3) {
;             const float sc = (part == 0) ? scale0 : 1.f;
;             const int row0 = u.pm * BM + wr * 64 + fr; const int col0 = (part == 0 ? 0 : 1024) + (u.pn & 3) * BM + wc * 32 + 8 * fq;
; #pragma unroll
;             for (int ai = 0; ai < 2; ++ai)
; #pragma unroll
;                 for (int m = 0; m < 4; ++m) { bf16_t* rowp = QZ + (size_t)(row0 + ai * HALF + m * 16) * 2048 + col0;
; #pragma unroll
;                     for (int bj = 0; bj < 2; ++bj) { f32x4 v0 = acc[ai][bj][m][0] * sc, v1 = acc[ai][bj][m][1] * sc;
;                         u32x4 w; w.x = cvt_pk_bf16(v0[0], v0[1]); w.y = cvt_pk_bf16(v0[2], v0[3]); w.z = cvt_pk_bf16(v1[0], v1[1]); w.w = cvt_pk_bf16(v1[2], v1[3]);
;                         *(u32x4*)(rowp + bj * HALF) = w; } }
.LBB0_125:
	s_and_b64 s[8:9], s[38:39], exec
	s_cselect_b32 s8, 0, 0x400
	s_lshl_b32 s9, s97, 8
	s_and_b32 s9, s9, 0x300
	v_lshl_add_u32 v158, s72, 8, v151
	s_or_b32 s8, s8, s9
	v_ashrrev_i32_e32 v159, 31, v158
	v_or_b32_e32 v0, s8, v155
	v_lshlrev_b64 v[152:153], 12, v[158:159]
	v_cndmask_b32_e64 v150, 1.0, v237, s[38:39]
	v_lshl_add_u64 v[152:153], s[78:79], 0, v[152:153]
	v_lshlrev_b32_e32 v0, 1, v0
	v_lshl_add_u64 v[152:153], v[152:153], 0, v[0:1]
	v_pk_mul_f32 v[128:129], v[150:151], v[128:129] op_sel_hi:[0,1]
	v_pk_mul_f32 v[126:127], v[150:151], v[126:127] op_sel_hi:[0,1]
	v_pk_mul_f32 v[160:161], v[150:151], v[124:125] op_sel_hi:[0,1]
	v_pk_mul_f32 v[124:125], v[150:151], v[122:123] op_sel_hi:[0,1]
	v_cvt_pk_bf16_f32 v122, v126, v127
	v_cvt_pk_bf16_f32 v123, v128, v129
	v_cvt_pk_bf16_f32 v124, v124, v125
	v_cvt_pk_bf16_f32 v125, v160, v161
	global_store_dwordx4 v[152:153], v[122:125], off sc1
	v_pk_mul_f32 v[118:119], v[150:151], v[118:119] op_sel_hi:[0,1]
	v_pk_mul_f32 v[120:121], v[150:151], v[120:121] op_sel_hi:[0,1]
	v_pk_mul_f32 v[122:123], v[150:151], v[112:113] op_sel_hi:[0,1]
	v_pk_mul_f32 v[112:113], v[150:151], v[110:111] op_sel_hi:[0,1]
	v_cvt_pk_bf16_f32 v110, v118, v119
	v_cvt_pk_bf16_f32 v111, v120, v121
	v_cvt_pk_bf16_f32 v112, v112, v113
	v_cvt_pk_bf16_f32 v113, v122, v123
	global_store_dwordx4 v[152:153], v[110:113], off offset:256 sc1
	v_pk_mul_f32 v[114:115], v[150:151], v[114:115] op_sel_hi:[0,1]
	v_pk_mul_f32 v[102:103], v[150:151], v[102:103] op_sel_hi:[0,1]
	v_or_b32_e32 v110, 16, v158
	v_ashrrev_i32_e32 v111, 31, v110
	v_lshlrev_b64 v[110:111], 12, v[110:111]
	v_lshl_add_u64 v[110:111], s[78:79], 0, v[110:111]
	v_lshl_add_u64 v[110:111], v[110:111], 0, v[0:1]
	v_pk_mul_f32 v[112:113], v[150:151], v[116:117] op_sel_hi:[0,1]
	v_pk_mul_f32 v[116:117], v[150:151], v[108:109] op_sel_hi:[0,1]
	v_pk_mul_f32 v[108:109], v[150:151], v[106:107] op_sel_hi:[0,1]
	v_cvt_pk_bf16_f32 v106, v114, v115
	v_cvt_pk_bf16_f32 v107, v112, v113
	v_cvt_pk_bf16_f32 v108, v108, v109
	v_cvt_pk_bf16_f32 v109, v116, v117
	global_store_dwordx4 v[110:111], v[106:109], off sc1
	v_pk_mul_f32 v[104:105], v[150:151], v[104:105] op_sel_hi:[0,1]
	v_pk_mul_f32 v[98:99], v[150:151], v[98:99] op_sel_hi:[0,1]
	v_pk_mul_f32 v[106:107], v[150:151], v[96:97] op_sel_hi:[0,1]
	v_pk_mul_f32 v[96:97], v[150:151], v[94:95] op_sel_hi:[0,1]
	v_cvt_pk_bf16_f32 v94, v102, v103
	v_cvt_pk_bf16_f32 v95, v104, v105
	v_cvt_pk_bf16_f32 v96, v96, v97
	v_cvt_pk_bf16_f32 v97, v106, v107
	global_store_dwordx4 v[110:111], v[94:97], off offset:256 sc1
	v_pk_mul_f32 v[86:87], v[150:151], v[86:87] op_sel_hi:[0,1]
	v_pk_mul_f32 v[88:89], v[150:151], v[88:89] op_sel_hi:[0,1]
	v_or_b32_e32 v94, 32, v158
	v_ashrrev_i32_e32 v95, 31, v94
	v_lshlrev_b64 v[94:95], 12, v[94:95]
	v_lshl_add_u64 v[94:95], s[78:79], 0, v[94:95]
	v_lshl_add_u64 v[94:95], v[94:95], 0, v[0:1]
	v_pk_mul_f32 v[96:97], v[150:151], v[100:101] op_sel_hi:[0,1]
	v_pk_mul_f32 v[100:101], v[150:151], v[92:93] op_sel_hi:[0,1]
	v_pk_mul_f32 v[92:93], v[150:151], v[90:91] op_sel_hi:[0,1]
	v_cvt_pk_bf16_f32 v90, v98, v99
	v_cvt_pk_bf16_f32 v91, v96, v97
	v_cvt_pk_bf16_f32 v92, v92, v93
	v_cvt_pk_bf16_f32 v93, v100, v101
	global_store_dwordx4 v[94:95], v[90:93], off sc1
	v_pk_mul_f32 v[82:83], v[150:151], v[82:83] op_sel_hi:[0,1]
	v_pk_mul_f32 v[72:73], v[150:151], v[72:73] op_sel_hi:[0,1]
	v_pk_mul_f32 v[90:91], v[150:151], v[80:81] op_sel_hi:[0,1]
	v_pk_mul_f32 v[80:81], v[150:151], v[78:79] op_sel_hi:[0,1]
	v_cvt_pk_bf16_f32 v78, v86, v87
	v_cvt_pk_bf16_f32 v79, v88, v89
	v_cvt_pk_bf16_f32 v80, v80, v81
	v_cvt_pk_bf16_f32 v81, v90, v91
	global_store_dwordx4 v[94:95], v[78:81], off offset:256 sc1
	v_pk_mul_f32 v[70:71], v[150:151], v[70:71] op_sel_hi:[0,1]
	s_mov_b64 s[8:9], 0x80000
	v_or_b32_e32 v78, 48, v158
	v_ashrrev_i32_e32 v79, 31, v78
	v_lshlrev_b64 v[78:79], 12, v[78:79]
	v_lshl_add_u64 v[78:79], s[78:79], 0, v[78:79]
	v_lshl_add_u64 v[78:79], v[78:79], 0, v[0:1]
	v_pk_mul_f32 v[80:81], v[150:151], v[84:85] op_sel_hi:[0,1]
	v_pk_mul_f32 v[84:85], v[150:151], v[76:77] op_sel_hi:[0,1]
	v_pk_mul_f32 v[76:77], v[150:151], v[74:75] op_sel_hi:[0,1]
	v_cvt_pk_bf16_f32 v74, v82, v83
	v_cvt_pk_bf16_f32 v75, v80, v81
	v_cvt_pk_bf16_f32 v76, v76, v77
	v_cvt_pk_bf16_f32 v77, v84, v85
	global_store_dwordx4 v[78:79], v[74:77], off sc1
	v_pk_mul_f32 v[62:63], v[150:151], v[62:63] op_sel_hi:[0,1]
	v_pk_mul_f32 v[64:65], v[150:151], v[64:65] op_sel_hi:[0,1]
; __device__ __forceinline__ unsigned cvt_pk_bf16(float lo, float hi) { unsigned r; asm volatile("v_cvt_pk_bf16_f32 %0, %1, %2" : "=v"(r) : "v"(lo), "v"(hi)); return r; }
;     __device__ __forceinline__ void operator()(const f32x4 (&acc)[2][2][4][2], const Unit& u, int wr, int wc, int fr, int fq) const {
;         const int part = u.pn >> 2;
;         if (part == 0 || part == 3) {
;             const float sc = (part == 0) ? scale0 : 1.f;
;             const int row0 = u.pm * BM + wr * 64 + fr; const int col0 = (part == 0 ? 0 : 1024) + (u.pn & 3) * BM + wc * 32 + 8 * fq;
; #pragma unroll
;             for (int ai = 0; ai < 2; ++ai)
; #pragma unroll
;                 for (int m = 0; m < 4; ++m) { bf16_t* rowp = QZ + (size_t)(row0 + ai * HALF + m * 16) * 2048 + col0;
; #pragma unroll
;                     for (int bj = 0; bj < 2; ++bj) { f32x4 v0 = acc[ai][bj][m][0] * sc, v1 = acc[ai][bj][m][1] * sc;
;                         u32x4 w; w.x = cvt_pk_bf16(v0[0], v0[1]); w.y = cvt_pk_bf16(v0[2], v0[3]); w.z = cvt_pk_bf16(v1[0], v1[1]); w.w = cvt_pk_bf16(v1[2], v1[3]);
;                         *(u32x4*)(rowp + bj * HALF) = w; } }
	v_pk_mul_f32 v[74:75], v[150:151], v[68:69] op_sel_hi:[0,1]
	v_pk_mul_f32 v[68:69], v[150:151], v[66:67] op_sel_hi:[0,1]
	v_cvt_pk_bf16_f32 v66, v70, v71
	v_cvt_pk_bf16_f32 v67, v72, v73
	v_cvt_pk_bf16_f32 v68, v68, v69
	v_cvt_pk_bf16_f32 v69, v74, v75
	global_store_dwordx4 v[78:79], v[66:69], off offset:256 sc1
	v_pk_mul_f32 v[56:57], v[150:151], v[56:57] op_sel_hi:[0,1]
	v_pk_mul_f32 v[54:55], v[150:151], v[54:55] op_sel_hi:[0,1]
	v_lshl_add_u64 v[66:67], v[152:153], 0, s[8:9]
	s_mov_b32 s8, 0x80000
	v_pk_mul_f32 v[68:69], v[150:151], v[60:61] op_sel_hi:[0,1]
	v_pk_mul_f32 v[60:61], v[150:151], v[58:59] op_sel_hi:[0,1]
	v_cvt_pk_bf16_f32 v58, v62, v63
	v_add_co_u32_e32 v62, vcc, s8, v152
	v_cvt_pk_bf16_f32 v59, v64, v65
	v_cvt_pk_bf16_f32 v60, v60, v61
	v_cvt_pk_bf16_f32 v61, v68, v69
	s_mov_b64 s[8:9], 0x90000
	s_nop 0
	v_addc_co_u32_e32 v63, vcc, 0, v153, vcc
	global_store_dwordx4 v[62:63], v[58:61], off sc1
	v_pk_mul_f32 v[50:51], v[150:151], v[50:51] op_sel_hi:[0,1]
	v_pk_mul_f32 v[40:41], v[150:151], v[40:41] op_sel_hi:[0,1]
	v_pk_mul_f32 v[58:59], v[150:151], v[48:49] op_sel_hi:[0,1]
	v_pk_mul_f32 v[48:49], v[150:151], v[46:47] op_sel_hi:[0,1]
	v_cvt_pk_bf16_f32 v46, v54, v55
	v_cvt_pk_bf16_f32 v47, v56, v57
	v_cvt_pk_bf16_f32 v48, v48, v49
	v_cvt_pk_bf16_f32 v49, v58, v59
	global_store_dwordx4 v[66:67], v[46:49], off offset:256 sc1
	v_pk_mul_f32 v[38:39], v[150:151], v[38:39] op_sel_hi:[0,1]
	v_pk_mul_f32 v[34:35], v[150:151], v[34:35] op_sel_hi:[0,1]
	v_lshl_add_u64 v[46:47], v[152:153], 0, s[8:9]
	v_pk_mul_f32 v[48:49], v[150:151], v[52:53] op_sel_hi:[0,1]
	s_mov_b32 s8, 0x90000
	v_pk_mul_f32 v[52:53], v[150:151], v[44:45] op_sel_hi:[0,1]
	v_pk_mul_f32 v[44:45], v[150:151], v[42:43] op_sel_hi:[0,1]
	v_cvt_pk_bf16_f32 v42, v50, v51
	v_cvt_pk_bf16_f32 v43, v48, v49
	v_add_co_u32_e32 v48, vcc, s8, v152
	v_cvt_pk_bf16_f32 v44, v44, v45
	v_cvt_pk_bf16_f32 v45, v52, v53
	s_mov_b64 s[8:9], 0xa0000
	s_nop 0
	v_addc_co_u32_e32 v49, vcc, 0, v153, vcc
	global_store_dwordx4 v[48:49], v[42:45], off sc1
	v_pk_mul_f32 v[24:25], v[150:151], v[24:25] op_sel_hi:[0,1]
	v_pk_mul_f32 v[22:23], v[150:151], v[22:23] op_sel_hi:[0,1]
	v_pk_mul_f32 v[42:43], v[150:151], v[32:33] op_sel_hi:[0,1]
	v_pk_mul_f32 v[32:33], v[150:151], v[30:31] op_sel_hi:[0,1]
	v_cvt_pk_bf16_f32 v30, v38, v39
	v_cvt_pk_bf16_f32 v31, v40, v41
	v_cvt_pk_bf16_f32 v32, v32, v33
	v_cvt_pk_bf16_f32 v33, v42, v43
	global_store_dwordx4 v[46:47], v[30:33], off offset:256 sc1
	v_pk_mul_f32 v[18:19], v[150:151], v[18:19] op_sel_hi:[0,1]
	v_pk_mul_f32 v[8:9], v[150:151], v[8:9] op_sel_hi:[0,1]
	v_lshl_add_u64 v[30:31], v[152:153], 0, s[8:9]
	v_pk_mul_f32 v[32:33], v[150:151], v[36:37] op_sel_hi:[0,1]
	s_mov_b32 s8, 0xa0000
	v_pk_mul_f32 v[36:37], v[150:151], v[28:29] op_sel_hi:[0,1]
	v_pk_mul_f32 v[28:29], v[150:151], v[26:27] op_sel_hi:[0,1]
	v_cvt_pk_bf16_f32 v26, v34, v35
	v_cvt_pk_bf16_f32 v27, v32, v33
	v_add_co_u32_e32 v32, vcc, s8, v152
	v_cvt_pk_bf16_f32 v28, v28, v29
	v_cvt_pk_bf16_f32 v29, v36, v37
	s_mov_b64 s[8:9], 0xb0000
	s_nop 0
	v_addc_co_u32_e32 v33, vcc, 0, v153, vcc
	global_store_dwordx4 v[32:33], v[26:29], off sc1
	v_pk_mul_f32 v[6:7], v[150:151], v[6:7] op_sel_hi:[0,1]
	s_nop 0
	v_pk_mul_f32 v[26:27], v[150:151], v[16:17] op_sel_hi:[0,1]
	v_pk_mul_f32 v[16:17], v[150:151], v[14:15] op_sel_hi:[0,1]
	v_cvt_pk_bf16_f32 v14, v22, v23
	v_cvt_pk_bf16_f32 v15, v24, v25
	v_cvt_pk_bf16_f32 v16, v16, v17
	v_cvt_pk_bf16_f32 v17, v26, v27
	global_store_dwordx4 v[30:31], v[14:17], off offset:256 sc1
	s_nop 1
	v_lshl_add_u64 v[14:15], v[152:153], 0, s[8:9]
	v_pk_mul_f32 v[16:17], v[150:151], v[20:21] op_sel_hi:[0,1]
	s_mov_b32 s8, 0xb0000
	v_pk_mul_f32 v[20:21], v[150:151], v[12:13] op_sel_hi:[0,1]
	v_pk_mul_f32 v[12:13], v[150:151], v[10:11] op_sel_hi:[0,1]
	v_cvt_pk_bf16_f32 v10, v18, v19
	v_cvt_pk_bf16_f32 v11, v16, v17
	v_add_co_u32_e32 v16, vcc, s8, v152
	v_cvt_pk_bf16_f32 v12, v12, v13
	v_cvt_pk_bf16_f32 v13, v20, v21
	s_nop 1
	v_addc_co_u32_e32 v17, vcc, 0, v153, vcc
	global_store_dwordx4 v[16:17], v[10:13], off sc1
	s_nop 1
	v_pk_mul_f32 v[10:11], v[150:151], v[4:5] op_sel_hi:[0,1]
	v_pk_mul_f32 v[4:5], v[150:151], v[2:3] op_sel_hi:[0,1]
	v_cvt_pk_bf16_f32 v2, v6, v7
	v_cvt_pk_bf16_f32 v3, v8, v9
	v_cvt_pk_bf16_f32 v4, v4, v5
	v_cvt_pk_bf16_f32 v5, v10, v11
	global_store_dwordx4 v[14:15], v[2:5], off offset:256 sc1
	s_andn2_b64 vcc, exec, s[36:37]
	s_mov_b64 s[8:9], -1
	s_cbranch_vccnz .LBB0_106

; __device__ __forceinline__ unsigned cvt_pk_bf16(float lo, float hi) { unsigned r; asm volatile("v_cvt_pk_bf16_f32 %0, %1, %2" : "=v"(r) : "v"(lo), "v"(hi)); return r; }
; __device__ __forceinline__ float silu_f(float z) { return z * __builtin_amdgcn_rcpf(1.0f + __builtin_amdgcn_exp2f(-1.4426950408889634f * z)); }
;     __device__ __forceinline__ void operator()(const f32x4 (&acc)[2][2][4][2], const Unit& u, int wr, int wc, int fr, int fq) const {
;         const int row0 = u.pm * BM + wr * 64 + fr;
;         const bool isg = wc >= 2;
;         bf16_t* base = (isg ? Gb : Vb) + u.pn * 64 + (wc & 1) * 32 + 8 * fq;
; #pragma unroll
;         for (int ai = 0; ai < 2; ++ai)
; #pragma unroll
;             for (int m = 0; m < 4; ++m) { bf16_t* rowp = base + (size_t)(row0 + ai * HALF + m * 16) * 1024;
;                 f32x4 a0 = acc[ai][0][m][0], a1 = acc[ai][0][m][1], b0 = acc[ai][1][m][0], b1 = acc[ai][1][m][1];
;                 if (isg) {
; #pragma unroll
;                     for (int e = 0; e < 4; ++e) { b0[e] = silu_f(b0[e]); b1[e] = silu_f(b1[e]); }
;                 }
;                 const f32x4 v0 = a0 * b0, v1 = a1 * b1;
;                 u32x4 w; w.x = cvt_pk_bf16(v0[0], v0[1]); w.y = cvt_pk_bf16(v0[2], v0[3]); w.z = cvt_pk_bf16(v1[0], v1[1]); w.w = cvt_pk_bf16(v1[2], v1[3]);
;                 *(u32x4*)rowp = w; }
.LBB0_149:
	v_lshl_add_u32 v142, s23, 8, v146
	s_lshl_b32 s8, s22, 6
	s_ashr_i32 s9, s8, 31
	v_ashrrev_i32_e32 v143, 31, v142
	v_lshl_add_u64 v[144:145], s[8:9], 1, v[136:137]
	v_lshlrev_b64 v[150:151], 11, v[142:143]
	v_lshl_add_u64 v[150:151], v[144:145], 0, v[150:151]
	v_pk_mul_f32 v[124:125], v[124:125], v[116:117]
	v_pk_mul_f32 v[116:117], v[122:123], v[114:115]
	s_and_b64 vcc, exec, s[38:39]
	v_pk_mul_f32 v[120:121], v[128:129], v[120:121]
	v_pk_mul_f32 v[118:119], v[126:127], v[118:119]
	s_nop 0
	v_cvt_pk_bf16_f32 v114, v118, v119
	v_cvt_pk_bf16_f32 v115, v120, v121
	v_cvt_pk_bf16_f32 v116, v116, v117
	v_cvt_pk_bf16_f32 v117, v124, v125
	global_store_dwordx4 v[150:151], v[114:117], off sc1
	s_cbranch_vccnz .LBB0_151
	s_nop 0
	v_mul_f32_e32 v115, 0xbfb8aa3b, v98
	v_exp_f32_e32 v115, v115
	v_mul_f32_e32 v114, 0xbfb8aa3b, v102
	v_exp_f32_e32 v114, v114
	v_mul_f32_e32 v119, 0xbfb8aa3b, v100
	v_add_f32_e32 v115, 1.0, v115
	v_rcp_f32_e32 v116, v115
	v_mul_f32_e32 v115, 0xbfb8aa3b, v103
	v_exp_f32_e32 v115, v115
	v_add_f32_e32 v114, 1.0, v114
	v_exp_f32_e32 v119, v119
	v_rcp_f32_e32 v114, v114
	v_add_f32_e32 v115, 1.0, v115
	v_rcp_f32_e32 v115, v115
	v_add_f32_e32 v119, 1.0, v119
	v_mul_f32_e32 v117, 0xbfb8aa3b, v99
	v_mul_f32_e32 v118, 0xbfb8aa3b, v104
	v_rcp_f32_e32 v120, v119
	v_mul_f32_e32 v119, 0xbfb8aa3b, v105
	v_pk_mul_f32 v[102:103], v[102:103], v[114:115]
	v_mul_f32_e32 v114, 0xbfb8aa3b, v101
	v_exp_f32_e32 v117, v117
	v_exp_f32_e32 v118, v118
	v_exp_f32_e32 v119, v119
	v_exp_f32_e32 v114, v114
	v_add_f32_e32 v117, 1.0, v117
	v_add_f32_e32 v118, 1.0, v118
	v_add_f32_e32 v119, 1.0, v119
	v_add_f32_e32 v114, 1.0, v114
	v_rcp_f32_e32 v117, v117
	v_rcp_f32_e32 v118, v118
	v_rcp_f32_e32 v119, v119
	v_rcp_f32_e32 v121, v114
	v_pk_mul_f32 v[98:99], v[98:99], v[116:117]
	v_pk_mul_f32 v[104:105], v[104:105], v[118:119]
	v_pk_mul_f32 v[100:101], v[100:101], v[120:121]
.LBB0_151:
	s_nop 0
	v_or_b32_e32 v114, 16, v142
	v_ashrrev_i32_e32 v115, 31, v114
	v_lshlrev_b64 v[114:115], 11, v[114:115]
	v_lshl_add_u64 v[114:115], v[144:145], 0, v[114:115]
	v_pk_mul_f32 v[108:109], v[108:109], v[100:101]
	v_pk_mul_f32 v[100:101], v[106:107], v[98:99]
	s_and_b64 vcc, exec, s[38:39]
	v_pk_mul_f32 v[104:105], v[112:113], v[104:105]
	v_pk_mul_f32 v[102:103], v[110:111], v[102:103]
	s_nop 0
	v_cvt_pk_bf16_f32 v98, v102, v103
	v_cvt_pk_bf16_f32 v99, v104, v105
	v_cvt_pk_bf16_f32 v100, v100, v101
	v_cvt_pk_bf16_f32 v101, v108, v109
	global_store_dwordx4 v[114:115], v[98:101], off sc1
	s_cbranch_vccnz .LBB0_153
	s_nop 0
	v_mul_f32_e32 v99, 0xbfb8aa3b, v82
	v_exp_f32_e32 v99, v99
	v_mul_f32_e32 v98, 0xbfb8aa3b, v86
	v_exp_f32_e32 v98, v98
	v_mul_f32_e32 v103, 0xbfb8aa3b, v84
	v_add_f32_e32 v99, 1.0, v99
	v_rcp_f32_e32 v100, v99
	v_mul_f32_e32 v99, 0xbfb8aa3b, v87
	v_exp_f32_e32 v99, v99
	v_add_f32_e32 v98, 1.0, v98
	v_exp_f32_e32 v103, v103
	v_rcp_f32_e32 v98, v98
	v_add_f32_e32 v99, 1.0, v99
	v_rcp_f32_e32 v99, v99
	v_add_f32_e32 v103, 1.0, v103
	v_mul_f32_e32 v101, 0xbfb8aa3b, v83
	v_mul_f32_e32 v102, 0xbfb8aa3b, v88
	v_rcp_f32_e32 v104, v103
	v_mul_f32_e32 v103, 0xbfb8aa3b, v89
	v_pk_mul_f32 v[86:87], v[86:87], v[98:99]
	v_mul_f32_e32 v98, 0xbfb8aa3b, v85
	v_exp_f32_e32 v101, v101
	v_exp_f32_e32 v102, v102
	v_exp_f32_e32 v103, v103
	v_exp_f32_e32 v98, v98
	v_add_f32_e32 v101, 1.0, v101
	v_add_f32_e32 v102, 1.0, v102
	v_add_f32_e32 v103, 1.0, v103
	v_add_f32_e32 v98, 1.0, v98
	v_rcp_f32_e32 v101, v101
	v_rcp_f32_e32 v102, v102
	v_rcp_f32_e32 v103, v103
	v_rcp_f32_e32 v105, v98
	v_pk_mul_f32 v[82:83], v[82:83], v[100:101]
	v_pk_mul_f32 v[88:89], v[88:89], v[102:103]
	v_pk_mul_f32 v[84:85], v[84:85], v[104:105]
.LBB0_153:
	s_nop 0
	v_or_b32_e32 v98, 32, v142
	v_ashrrev_i32_e32 v99, 31, v98
	v_lshlrev_b64 v[98:99], 11, v[98:99]
	v_lshl_add_u64 v[98:99], v[144:145], 0, v[98:99]
	v_pk_mul_f32 v[92:93], v[92:93], v[84:85]
	v_pk_mul_f32 v[84:85], v[90:91], v[82:83]
	s_and_b64 vcc, exec, s[38:39]
	v_pk_mul_f32 v[88:89], v[96:97], v[88:89]
	v_pk_mul_f32 v[86:87], v[94:95], v[86:87]
	s_nop 0
	v_cvt_pk_bf16_f32 v82, v86, v87
	v_cvt_pk_bf16_f32 v83, v88, v89
	v_cvt_pk_bf16_f32 v84, v84, v85
	v_cvt_pk_bf16_f32 v85, v92, v93
	global_store_dwordx4 v[98:99], v[82:85], off sc1
	s_cbranch_vccnz .LBB0_155
	s_nop 0
	v_mul_f32_e32 v83, 0xbfb8aa3b, v66
	v_exp_f32_e32 v83, v83
	v_mul_f32_e32 v82, 0xbfb8aa3b, v70
	v_exp_f32_e32 v82, v82
	v_mul_f32_e32 v87, 0xbfb8aa3b, v68
	v_add_f32_e32 v83, 1.0, v83
	v_rcp_f32_e32 v84, v83
	v_mul_f32_e32 v83, 0xbfb8aa3b, v71
	v_exp_f32_e32 v83, v83
	v_add_f32_e32 v82, 1.0, v82
	v_exp_f32_e32 v87, v87
	v_rcp_f32_e32 v82, v82
	v_add_f32_e32 v83, 1.0, v83
	v_rcp_f32_e32 v83, v83
	v_add_f32_e32 v87, 1.0, v87
	v_mul_f32_e32 v85, 0xbfb8aa3b, v67
	v_mul_f32_e32 v86, 0xbfb8aa3b, v72
	v_rcp_f32_e32 v88, v87
	v_mul_f32_e32 v87, 0xbfb8aa3b, v73
	v_pk_mul_f32 v[70:71], v[70:71], v[82:83]
	v_mul_f32_e32 v82, 0xbfb8aa3b, v69
	v_exp_f32_e32 v85, v85
	v_exp_f32_e32 v86, v86
	v_exp_f32_e32 v87, v87
	v_exp_f32_e32 v82, v82
	v_add_f32_e32 v85, 1.0, v85
	v_add_f32_e32 v86, 1.0, v86
	v_add_f32_e32 v87, 1.0, v87
	v_add_f32_e32 v82, 1.0, v82
	v_rcp_f32_e32 v85, v85
	v_rcp_f32_e32 v86, v86
	v_rcp_f32_e32 v87, v87
	v_rcp_f32_e32 v89, v82
	v_pk_mul_f32 v[66:67], v[66:67], v[84:85]
	v_pk_mul_f32 v[72:73], v[72:73], v[86:87]
	v_pk_mul_f32 v[68:69], v[68:69], v[88:89]
; __device__ __forceinline__ unsigned cvt_pk_bf16(float lo, float hi) { unsigned r; asm volatile("v_cvt_pk_bf16_f32 %0, %1, %2" : "=v"(r) : "v"(lo), "v"(hi)); return r; }
; __device__ __forceinline__ float silu_f(float z) { return z * __builtin_amdgcn_rcpf(1.0f + __builtin_amdgcn_exp2f(-1.4426950408889634f * z)); }
;     __device__ __forceinline__ void operator()(const f32x4 (&acc)[2][2][4][2], const Unit& u, int wr, int wc, int fr, int fq) const {
;         const int row0 = u.pm * BM + wr * 64 + fr;
;         const bool isg = wc >= 2;
;         bf16_t* base = (isg ? Gb : Vb) + u.pn * 64 + (wc & 1) * 32 + 8 * fq;
; #pragma unroll
;         for (int ai = 0; ai < 2; ++ai)
; #pragma unroll
;             for (int m = 0; m < 4; ++m) { bf16_t* rowp = base + (size_t)(row0 + ai * HALF + m * 16) * 1024;
;                 f32x4 a0 = acc[ai][0][m][0], a1 = acc[ai][0][m][1], b0 = acc[ai][1][m][0], b1 = acc[ai][1][m][1];
;                 if (isg) {
; #pragma unroll
;                     for (int e = 0; e < 4; ++e) { b0[e] = silu_f(b0[e]); b1[e] = silu_f(b1[e]); }
;                 }
;                 const f32x4 v0 = a0 * b0, v1 = a1 * b1;
;                 u32x4 w; w.x = cvt_pk_bf16(v0[0], v0[1]); w.y = cvt_pk_bf16(v0[2], v0[3]); w.z = cvt_pk_bf16(v1[0], v1[1]); w.w = cvt_pk_bf16(v1[2], v1[3]);
;                 *(u32x4*)rowp = w; }
.LBB0_155:
	s_nop 0
	v_or_b32_e32 v82, 48, v142
	v_ashrrev_i32_e32 v83, 31, v82
	v_lshlrev_b64 v[82:83], 11, v[82:83]
	v_lshl_add_u64 v[82:83], v[144:145], 0, v[82:83]
	v_pk_mul_f32 v[76:77], v[76:77], v[68:69]
	v_pk_mul_f32 v[68:69], v[74:75], v[66:67]
	s_and_b64 vcc, exec, s[38:39]
	v_pk_mul_f32 v[72:73], v[80:81], v[72:73]
	v_pk_mul_f32 v[70:71], v[78:79], v[70:71]
	s_nop 0
	v_cvt_pk_bf16_f32 v66, v70, v71
	v_cvt_pk_bf16_f32 v67, v72, v73
	v_cvt_pk_bf16_f32 v68, v68, v69
	v_cvt_pk_bf16_f32 v69, v76, v77
	global_store_dwordx4 v[82:83], v[66:69], off sc1
	s_cbranch_vccnz .LBB0_157
	s_nop 0
	v_mul_f32_e32 v67, 0xbfb8aa3b, v50
	v_exp_f32_e32 v67, v67
	v_mul_f32_e32 v66, 0xbfb8aa3b, v54
	v_exp_f32_e32 v66, v66
	v_mul_f32_e32 v71, 0xbfb8aa3b, v52
	v_add_f32_e32 v67, 1.0, v67
	v_rcp_f32_e32 v68, v67
	v_mul_f32_e32 v67, 0xbfb8aa3b, v55
	v_exp_f32_e32 v67, v67
	v_add_f32_e32 v66, 1.0, v66
	v_exp_f32_e32 v71, v71
	v_rcp_f32_e32 v66, v66
	v_add_f32_e32 v67, 1.0, v67
	v_rcp_f32_e32 v67, v67
	v_add_f32_e32 v71, 1.0, v71
	v_mul_f32_e32 v69, 0xbfb8aa3b, v51
	v_mul_f32_e32 v70, 0xbfb8aa3b, v56
	v_rcp_f32_e32 v72, v71
	v_mul_f32_e32 v71, 0xbfb8aa3b, v57
	v_pk_mul_f32 v[54:55], v[54:55], v[66:67]
	v_mul_f32_e32 v66, 0xbfb8aa3b, v53
	v_exp_f32_e32 v69, v69
	v_exp_f32_e32 v70, v70
	v_exp_f32_e32 v71, v71
	v_exp_f32_e32 v66, v66
	v_add_f32_e32 v69, 1.0, v69
	v_add_f32_e32 v70, 1.0, v70
	v_add_f32_e32 v71, 1.0, v71
	v_add_f32_e32 v66, 1.0, v66
	v_rcp_f32_e32 v69, v69
	v_rcp_f32_e32 v70, v70
	v_rcp_f32_e32 v71, v71
	v_rcp_f32_e32 v73, v66
	v_pk_mul_f32 v[50:51], v[50:51], v[68:69]
	v_pk_mul_f32 v[56:57], v[56:57], v[70:71]
	v_pk_mul_f32 v[52:53], v[52:53], v[72:73]
.LBB0_157:
	s_nop 0
	v_lshlrev_b64 v[66:67], 11, v[142:143]
	v_lshl_add_u64 v[66:67], v[144:145], 0, v[66:67]
	v_pk_mul_f32 v[54:55], v[62:63], v[54:55]
	v_pk_mul_f32 v[60:61], v[60:61], v[52:53]
	v_pk_mul_f32 v[52:53], v[58:59], v[50:51]
	v_cvt_pk_bf16_f32 v50, v54, v55
	v_add_co_u32_e32 v54, vcc, 0x40000, v66
	v_pk_mul_f32 v[56:57], v[64:65], v[56:57]
	s_nop 0
	v_addc_co_u32_e32 v55, vcc, 0, v67, vcc
	s_and_b64 vcc, exec, s[38:39]
	v_cvt_pk_bf16_f32 v51, v56, v57
	v_cvt_pk_bf16_f32 v52, v52, v53
	v_cvt_pk_bf16_f32 v53, v60, v61
	global_store_dwordx4 v[54:55], v[50:53], off sc1
	s_cbranch_vccnz .LBB0_159
	s_nop 0
	v_mul_f32_e32 v51, 0xbfb8aa3b, v34
	v_exp_f32_e32 v51, v51
	v_mul_f32_e32 v50, 0xbfb8aa3b, v38
	v_exp_f32_e32 v50, v50
	v_mul_f32_e32 v55, 0xbfb8aa3b, v36
	v_add_f32_e32 v51, 1.0, v51
	v_rcp_f32_e32 v52, v51
	v_mul_f32_e32 v51, 0xbfb8aa3b, v39
	v_exp_f32_e32 v51, v51
	v_add_f32_e32 v50, 1.0, v50
	v_exp_f32_e32 v55, v55
	v_rcp_f32_e32 v50, v50
	v_add_f32_e32 v51, 1.0, v51
	v_rcp_f32_e32 v51, v51
	v_add_f32_e32 v55, 1.0, v55
	v_mul_f32_e32 v53, 0xbfb8aa3b, v35
	v_mul_f32_e32 v54, 0xbfb8aa3b, v40
	v_rcp_f32_e32 v56, v55
	v_mul_f32_e32 v55, 0xbfb8aa3b, v41
	v_pk_mul_f32 v[38:39], v[38:39], v[50:51]
	v_mul_f32_e32 v50, 0xbfb8aa3b, v37
	v_exp_f32_e32 v53, v53
	v_exp_f32_e32 v54, v54
	v_exp_f32_e32 v55, v55
	v_exp_f32_e32 v50, v50
	v_add_f32_e32 v53, 1.0, v53
	v_add_f32_e32 v54, 1.0, v54
	v_add_f32_e32 v55, 1.0, v55
	v_add_f32_e32 v50, 1.0, v50
	v_rcp_f32_e32 v53, v53
	v_rcp_f32_e32 v54, v54
	v_rcp_f32_e32 v55, v55
	v_rcp_f32_e32 v57, v50
	v_pk_mul_f32 v[34:35], v[34:35], v[52:53]
	v_pk_mul_f32 v[40:41], v[40:41], v[54:55]
	v_pk_mul_f32 v[36:37], v[36:37], v[56:57]
; __device__ __forceinline__ unsigned cvt_pk_bf16(float lo, float hi) { unsigned r; asm volatile("v_cvt_pk_bf16_f32 %0, %1, %2" : "=v"(r) : "v"(lo), "v"(hi)); return r; }
; __device__ __forceinline__ float silu_f(float z) { return z * __builtin_amdgcn_rcpf(1.0f + __builtin_amdgcn_exp2f(-1.4426950408889634f * z)); }
;     __device__ __forceinline__ void operator()(const f32x4 (&acc)[2][2][4][2], const Unit& u, int wr, int wc, int fr, int fq) const {
;         const int row0 = u.pm * BM + wr * 64 + fr;
;         const bool isg = wc >= 2;
;         bf16_t* base = (isg ? Gb : Vb) + u.pn * 64 + (wc & 1) * 32 + 8 * fq;
; #pragma unroll
;         for (int ai = 0; ai < 2; ++ai)
; #pragma unroll
;             for (int m = 0; m < 4; ++m) { bf16_t* rowp = base + (size_t)(row0 + ai * HALF + m * 16) * 1024;
;                 f32x4 a0 = acc[ai][0][m][0], a1 = acc[ai][0][m][1], b0 = acc[ai][1][m][0], b1 = acc[ai][1][m][1];
;                 if (isg) {
; #pragma unroll
;                     for (int e = 0; e < 4; ++e) { b0[e] = silu_f(b0[e]); b1[e] = silu_f(b1[e]); }
;                 }
;                 const f32x4 v0 = a0 * b0, v1 = a1 * b1;
;                 u32x4 w; w.x = cvt_pk_bf16(v0[0], v0[1]); w.y = cvt_pk_bf16(v0[2], v0[3]); w.z = cvt_pk_bf16(v1[0], v1[1]); w.w = cvt_pk_bf16(v1[2], v1[3]);
;                 *(u32x4*)rowp = w; }
.LBB0_159:
	v_pk_mul_f32 v[38:39], v[46:47], v[38:39]
	v_pk_mul_f32 v[44:45], v[44:45], v[36:37]
	v_pk_mul_f32 v[36:37], v[42:43], v[34:35]
	v_cvt_pk_bf16_f32 v34, v38, v39
	v_add_co_u32_e32 v38, vcc, 0x48000, v66
	v_pk_mul_f32 v[40:41], v[48:49], v[40:41]
	s_nop 0
	v_addc_co_u32_e32 v39, vcc, 0, v67, vcc
	s_and_b64 vcc, exec, s[38:39]
	v_cvt_pk_bf16_f32 v35, v40, v41
	v_cvt_pk_bf16_f32 v36, v36, v37
	v_cvt_pk_bf16_f32 v37, v44, v45
	global_store_dwordx4 v[38:39], v[34:37], off sc1
	s_cbranch_vccnz .LBB0_161
	s_nop 0
	v_mul_f32_e32 v35, 0xbfb8aa3b, v18
	v_exp_f32_e32 v35, v35
	v_mul_f32_e32 v34, 0xbfb8aa3b, v22
	v_exp_f32_e32 v34, v34
	v_mul_f32_e32 v39, 0xbfb8aa3b, v20
	v_add_f32_e32 v35, 1.0, v35
	v_rcp_f32_e32 v36, v35
	v_mul_f32_e32 v35, 0xbfb8aa3b, v23
	v_exp_f32_e32 v35, v35
	v_add_f32_e32 v34, 1.0, v34
	v_exp_f32_e32 v39, v39
	v_rcp_f32_e32 v34, v34
	v_add_f32_e32 v35, 1.0, v35
	v_rcp_f32_e32 v35, v35
	v_add_f32_e32 v39, 1.0, v39
	v_mul_f32_e32 v37, 0xbfb8aa3b, v19
	v_mul_f32_e32 v38, 0xbfb8aa3b, v24
	v_rcp_f32_e32 v40, v39
	v_mul_f32_e32 v39, 0xbfb8aa3b, v25
	v_pk_mul_f32 v[22:23], v[22:23], v[34:35]
	v_mul_f32_e32 v34, 0xbfb8aa3b, v21
	v_exp_f32_e32 v37, v37
	v_exp_f32_e32 v38, v38
	v_exp_f32_e32 v39, v39
	v_exp_f32_e32 v34, v34
	v_add_f32_e32 v37, 1.0, v37
	v_add_f32_e32 v38, 1.0, v38
	v_add_f32_e32 v39, 1.0, v39
	v_add_f32_e32 v34, 1.0, v34
	v_rcp_f32_e32 v37, v37
	v_rcp_f32_e32 v38, v38
	v_rcp_f32_e32 v39, v39
	v_rcp_f32_e32 v41, v34
	v_pk_mul_f32 v[18:19], v[18:19], v[36:37]
	v_pk_mul_f32 v[24:25], v[24:25], v[38:39]
	v_pk_mul_f32 v[20:21], v[20:21], v[40:41]
.LBB0_161:
	s_nop 0
	v_lshlrev_b64 v[34:35], 11, v[142:143]
	v_lshl_add_u64 v[34:35], v[144:145], 0, v[34:35]
	v_pk_mul_f32 v[22:23], v[30:31], v[22:23]
	v_pk_mul_f32 v[28:29], v[28:29], v[20:21]
	v_pk_mul_f32 v[20:21], v[26:27], v[18:19]
	v_cvt_pk_bf16_f32 v18, v22, v23
	v_add_co_u32_e32 v22, vcc, 0x50000, v34
	v_pk_mul_f32 v[24:25], v[32:33], v[24:25]
	s_nop 0
	v_addc_co_u32_e32 v23, vcc, 0, v35, vcc
	s_and_b64 vcc, exec, s[38:39]
	v_cvt_pk_bf16_f32 v19, v24, v25
	v_cvt_pk_bf16_f32 v20, v20, v21
	v_cvt_pk_bf16_f32 v21, v28, v29
	global_store_dwordx4 v[22:23], v[18:21], off sc1
	s_cbranch_vccnz .LBB0_163
	s_nop 0
	v_mul_f32_e32 v19, 0xbfb8aa3b, v2
	v_exp_f32_e32 v19, v19
	v_mul_f32_e32 v18, 0xbfb8aa3b, v6
	v_exp_f32_e32 v18, v18
	v_mul_f32_e32 v23, 0xbfb8aa3b, v4
	v_add_f32_e32 v19, 1.0, v19
	v_rcp_f32_e32 v20, v19
	v_mul_f32_e32 v19, 0xbfb8aa3b, v7
	v_exp_f32_e32 v19, v19
	v_add_f32_e32 v18, 1.0, v18
	v_exp_f32_e32 v23, v23
	v_rcp_f32_e32 v18, v18
	v_add_f32_e32 v19, 1.0, v19
	v_rcp_f32_e32 v19, v19
	v_add_f32_e32 v23, 1.0, v23
	v_mul_f32_e32 v21, 0xbfb8aa3b, v3
	v_mul_f32_e32 v22, 0xbfb8aa3b, v8
	v_rcp_f32_e32 v24, v23
	v_mul_f32_e32 v23, 0xbfb8aa3b, v9
	v_pk_mul_f32 v[6:7], v[6:7], v[18:19]
	v_mul_f32_e32 v18, 0xbfb8aa3b, v5
	v_exp_f32_e32 v21, v21
	v_exp_f32_e32 v22, v22
	v_exp_f32_e32 v23, v23
	v_exp_f32_e32 v18, v18
	v_add_f32_e32 v21, 1.0, v21
	v_add_f32_e32 v22, 1.0, v22
	v_add_f32_e32 v23, 1.0, v23
	v_add_f32_e32 v18, 1.0, v18
	v_rcp_f32_e32 v21, v21
	v_rcp_f32_e32 v22, v22
	v_rcp_f32_e32 v23, v23
	v_rcp_f32_e32 v25, v18
	v_pk_mul_f32 v[2:3], v[2:3], v[20:21]
	v_pk_mul_f32 v[8:9], v[8:9], v[22:23]
	v_pk_mul_f32 v[4:5], v[4:5], v[24:25]
.LBB0_163:
	v_pk_mul_f32 v[6:7], v[14:15], v[6:7]
	v_pk_mul_f32 v[12:13], v[12:13], v[4:5]
	v_pk_mul_f32 v[4:5], v[10:11], v[2:3]
	v_cvt_pk_bf16_f32 v2, v6, v7
	v_add_co_u32_e32 v6, vcc, 0x58000, v34
	s_mov_b64 s[8:9], -1
	s_nop 0
	v_addc_co_u32_e32 v7, vcc, 0, v35, vcc
	s_andn2_b64 vcc, exec, s[36:37]
	v_pk_mul_f32 v[8:9], v[16:17], v[8:9]
	s_nop 0
	v_cvt_pk_bf16_f32 v3, v8, v9
	v_cvt_pk_bf16_f32 v4, v4, v5
	v_cvt_pk_bf16_f32 v5, v12, v13
	global_store_dwordx4 v[6:7], v[2:5], off sc1
	s_cbranch_vccnz .LBB0_136
	s_andn2_b64 vcc, exec, s[4:5]
	s_cbranch_vccnz .LBB0_135
	s_barrier
	s_branch .LBB0_135

; #define GAS __attribute__((address_space(1)))
; __device__ __forceinline__ unsigned pk2(float lo, float hi) { return f2bf(lo) | (f2bf(hi) << 16); }
; __device__ __forceinline__ float bfl(unsigned w) { return __uint_as_float(w << 16); }
; __device__ __forceinline__ float bfh(unsigned w) { return __uint_as_float(w & 0xffff0000u); }
; __device__ __forceinline__ void conv_pass(const bf16* Vb, const bf16* Gb, const float* cw  , bf16* Y, int gtid, int nthreads) {
;     ...
;     for (int row = r0; row < M; row += NRC * rstep) {
;         v4u c2[NRC], c1[NRC], c0[NRC], gg[NRC]; size_t off[NRC];
; #pragma unroll
;         for (int k = 0; k < NRC; ++k) { const int rw = row + k * rstep; const int rr = rw < M ? rw : row; const int s = rr & (T - 1);
;             off[k] = (size_t)rr * D + chunk * 8;
;             c2[k] = *(const GAS v4u*)(Vb + off[k]); c1[k] = (v4u){0u, 0u, 0u, 0u}; c0[k] = (v4u){0u, 0u, 0u, 0u};
;             if (s >= 1) c1[k] = *(const GAS v4u*)(Vb + off[k] - D);
;             if (s >= 2) c0[k] = *(const GAS v4u*)(Vb + off[k] - 2 * D);
;             gg[k] = *(const GAS v4u*)(Gb + off[k]); }
; #pragma unroll
;         for (int k = 0; k < NRC; ++k) { if (row + k * rstep < M) { v4u o;
; #pragma unroll
;             for (int q = 0; q < 4; ++q) {
;                 const float ylo = bfl(gg[k][q]) * (w0[2 * q] * bfl(c0[k][q]) + w1[2 * q] * bfl(c1[k][q]) + w2[2 * q] * bfl(c2[k][q]));
;                 const float yhi = bfh(gg[k][q]) * (w0[2 * q + 1] * bfh(c0[k][q]) + w1[2 * q + 1] * bfh(c1[k][q]) + w2[2 * q + 1] * bfh(c2[k][q]));
;                 o[q] = pk2(ylo, yhi);
;             }
;             *(GAS v4u*)(Y + off[k]) = o; } }
.LBB0_279:
	s_or_b64 exec, exec, s[8:9]
	v_lshl_add_u64 v[46:47], v[12:13], 1, s[0:1]
	global_load_dwordx4 v[46:49], v[46:47], off
	s_waitcnt vmcnt(7)
	v_lshlrev_b32_e32 v105, 16, v67
	v_lshlrev_b32_e32 v104, 16, v66
	v_and_b32_e32 v67, 0xffff0000, v67
	v_and_b32_e32 v66, 0xffff0000, v66
	v_lshlrev_b32_e32 v103, 16, v71
	v_lshlrev_b32_e32 v102, 16, v70
	v_pk_mul_f32 v[104:105], v[86:87], v[104:105]
	v_and_b32_e32 v71, 0xffff0000, v71
	v_and_b32_e32 v70, 0xffff0000, v70
	v_pk_mul_f32 v[66:67], v[2:3], v[66:67]
	v_pk_fma_f32 v[102:103], v[6:7], v[102:103], v[104:105]
	v_lshlrev_b32_e32 v105, 16, v63
	v_lshlrev_b32_e32 v104, 16, v62
	v_pk_fma_f32 v[66:67], v[84:85], v[70:71], v[66:67]
	v_and_b32_e32 v63, 0xffff0000, v63
	v_and_b32_e32 v62, 0xffff0000, v62
	s_waitcnt vmcnt(6)
	v_lshlrev_b32_e32 v101, 16, v79
	v_lshlrev_b32_e32 v100, 16, v78
	v_and_b32_e32 v79, 0xffff0000, v79
	v_and_b32_e32 v78, 0xffff0000, v78
	v_pk_fma_f32 v[62:63], v[82:83], v[62:63], v[66:67]
	v_lshlrev_b32_e32 v71, 16, v73
	v_pk_mul_f32 v[62:63], v[62:63], v[78:79]
	v_lshlrev_b32_e32 v79, 16, v69
	v_lshlrev_b32_e32 v78, 16, v68
	v_lshlrev_b32_e32 v70, 16, v72
	v_pk_mul_f32 v[78:79], v[90:91], v[78:79]
	v_and_b32_e32 v69, 0xffff0000, v69
	v_and_b32_e32 v68, 0xffff0000, v68
	v_pk_fma_f32 v[70:71], v[14:15], v[70:71], v[78:79]
	v_lshlrev_b32_e32 v79, 16, v65
	v_lshlrev_b32_e32 v78, 16, v64
	v_and_b32_e32 v73, 0xffff0000, v73
	v_and_b32_e32 v72, 0xffff0000, v72
	v_pk_mul_f32 v[68:69], v[10:11], v[68:69]
	v_lshlrev_b32_e32 v67, 16, v81
	v_lshlrev_b32_e32 v66, 16, v80
	v_pk_fma_f32 v[70:71], v[16:17], v[78:79], v[70:71]
	v_pk_fma_f32 v[68:69], v[88:89], v[72:73], v[68:69]
	v_and_b32_e32 v65, 0xffff0000, v65
	v_and_b32_e32 v64, 0xffff0000, v64
	v_pk_mul_f32 v[66:67], v[70:71], v[66:67]
	v_and_b32_e32 v71, 0xffff0000, v81
	v_and_b32_e32 v70, 0xffff0000, v80
	v_pk_fma_f32 v[64:65], v[4:5], v[64:65], v[68:69]
	v_pk_fma_f32 v[102:103], v[8:9], v[104:105], v[102:103]
	v_pk_mul_f32 v[64:65], v[64:65], v[70:71]
	v_pk_mul_f32 v[100:101], v[102:103], v[100:101]
	v_bfe_u32 v68, v65, 16, 1
	v_bfe_u32 v69, v64, 16, 1
	v_bfe_u32 v70, v63, 16, 1
	v_bfe_u32 v71, v62, 16, 1
	v_add3_u32 v62, v62, v71, s44
	v_add3_u32 v63, v63, v70, s44
	v_add3_u32 v64, v64, v69, s44
	v_add3_u32 v65, v65, v68, s44
	v_bfe_u32 v68, v100, 16, 1
	v_bfe_u32 v69, v101, 16, 1
	v_bfe_u32 v70, v66, 16, 1
	v_bfe_u32 v71, v67, 16, 1
	v_add3_u32 v67, v67, v71, s44
	v_add3_u32 v66, v66, v70, s44
	v_add3_u32 v69, v101, v69, s44
	v_add3_u32 v68, v100, v68, s44
	v_lshrrev_b32_e32 v68, 16, v68
	v_lshrrev_b32_e32 v69, 16, v69
	v_lshrrev_b32_e32 v66, 16, v66
	v_lshrrev_b32_e32 v67, 16, v67
	v_and_or_b32 v65, v65, s45, v67
	v_and_or_b32 v64, v64, s45, v66
	v_and_or_b32 v63, v63, s45, v69
	v_and_or_b32 v62, v62, s45, v68
	v_lshl_add_u64 v[66:67], v[96:97], 1, s[76:77]
	global_store_dwordx4 v[66:67], v[62:65], off sc1
	s_and_saveexec_b64 s[8:9], s[38:39]
	s_cbranch_execnz .LBB0_282
	s_or_b64 exec, exec, s[8:9]
	s_and_saveexec_b64 s[8:9], s[36:37]
	s_cbranch_execnz .LBB0_283

; #define GAS __attribute__((address_space(1)))
; __device__ __forceinline__ unsigned pk2(float lo, float hi) { return f2bf(lo) | (f2bf(hi) << 16); }
; __device__ __forceinline__ float bfl(unsigned w) { return __uint_as_float(w << 16); }
; __device__ __forceinline__ float bfh(unsigned w) { return __uint_as_float(w & 0xffff0000u); }
; __device__ __forceinline__ void conv_pass(const bf16* Vb, const bf16* Gb, const float* cw  , bf16* Y, int gtid, int nthreads) {
;     ...
;         for (int k = 0; k < NRC; ++k) { if (row + k * rstep < M) { v4u o;
; #pragma unroll
;             for (int q = 0; q < 4; ++q) {
;                 const float ylo = bfl(gg[k][q]) * (w0[2 * q] * bfl(c0[k][q]) + w1[2 * q] * bfl(c1[k][q]) + w2[2 * q] * bfl(c2[k][q]));
;                 const float yhi = bfh(gg[k][q]) * (w0[2 * q + 1] * bfh(c0[k][q]) + w1[2 * q + 1] * bfh(c1[k][q]) + w2[2 * q + 1] * bfh(c2[k][q]));
;                 o[q] = pk2(ylo, yhi);
;             }
;             *(GAS v4u*)(Y + off[k]) = o; } }
.LBB0_282:
	s_waitcnt vmcnt(6)
	v_lshlrev_b32_e32 v67, 16, v51
	v_lshlrev_b32_e32 v66, 16, v50
	v_lshlrev_b32_e32 v65, 16, v55
	v_lshlrev_b32_e32 v64, 16, v54
	v_pk_mul_f32 v[66:67], v[86:87], v[66:67]
	v_and_b32_e32 v51, 0xffff0000, v51
	v_and_b32_e32 v50, 0xffff0000, v50
	v_pk_fma_f32 v[64:65], v[6:7], v[64:65], v[66:67]
	v_lshlrev_b32_e32 v67, 16, v43
	v_lshlrev_b32_e32 v66, 16, v42
	v_and_b32_e32 v55, 0xffff0000, v55
	v_and_b32_e32 v54, 0xffff0000, v54
	v_pk_mul_f32 v[50:51], v[2:3], v[50:51]
	s_waitcnt vmcnt(5)
	v_lshlrev_b32_e32 v63, 16, v75
	v_lshlrev_b32_e32 v62, 16, v74
	v_pk_fma_f32 v[64:65], v[8:9], v[66:67], v[64:65]
	v_pk_fma_f32 v[50:51], v[84:85], v[54:55], v[50:51]
	v_and_b32_e32 v43, 0xffff0000, v43
	v_and_b32_e32 v42, 0xffff0000, v42
	v_pk_mul_f32 v[62:63], v[64:65], v[62:63]
	v_and_b32_e32 v65, 0xffff0000, v75
	v_and_b32_e32 v64, 0xffff0000, v74
	v_pk_fma_f32 v[42:43], v[82:83], v[42:43], v[50:51]
	v_lshlrev_b32_e32 v55, 16, v57
	v_pk_mul_f32 v[42:43], v[42:43], v[64:65]
	v_lshlrev_b32_e32 v65, 16, v53
	v_lshlrev_b32_e32 v64, 16, v52
	v_lshlrev_b32_e32 v54, 16, v56
	v_pk_mul_f32 v[64:65], v[90:91], v[64:65]
	v_and_b32_e32 v53, 0xffff0000, v53
	v_and_b32_e32 v52, 0xffff0000, v52
	v_pk_fma_f32 v[54:55], v[14:15], v[54:55], v[64:65]
	v_lshlrev_b32_e32 v65, 16, v45
	v_lshlrev_b32_e32 v64, 16, v44
	v_and_b32_e32 v57, 0xffff0000, v57
	v_and_b32_e32 v56, 0xffff0000, v56
	v_pk_mul_f32 v[52:53], v[10:11], v[52:53]
	v_lshlrev_b32_e32 v51, 16, v77
	v_lshlrev_b32_e32 v50, 16, v76
	v_pk_fma_f32 v[54:55], v[16:17], v[64:65], v[54:55]
	v_pk_fma_f32 v[52:53], v[88:89], v[56:57], v[52:53]
	v_and_b32_e32 v45, 0xffff0000, v45
	v_and_b32_e32 v44, 0xffff0000, v44
	v_pk_mul_f32 v[50:51], v[54:55], v[50:51]
	v_and_b32_e32 v55, 0xffff0000, v77
	v_and_b32_e32 v54, 0xffff0000, v76
	v_pk_fma_f32 v[44:45], v[4:5], v[44:45], v[52:53]
	s_nop 0
	v_pk_mul_f32 v[44:45], v[44:45], v[54:55]
	v_bfe_u32 v54, v43, 16, 1
	v_bfe_u32 v52, v45, 16, 1
	v_bfe_u32 v53, v44, 16, 1
	v_bfe_u32 v55, v42, 16, 1
	v_add3_u32 v42, v42, v55, s44
	v_add3_u32 v43, v43, v54, s44
	v_add3_u32 v44, v44, v53, s44
	v_add3_u32 v45, v45, v52, s44
	v_bfe_u32 v52, v62, 16, 1
	v_bfe_u32 v53, v63, 16, 1
	v_bfe_u32 v54, v50, 16, 1
	v_bfe_u32 v55, v51, 16, 1
	v_add3_u32 v51, v51, v55, s44
	v_add3_u32 v50, v50, v54, s44
	v_add3_u32 v53, v63, v53, s44
	v_add3_u32 v52, v62, v52, s44
	v_lshrrev_b32_e32 v52, 16, v52
	v_lshrrev_b32_e32 v53, 16, v53
	v_lshrrev_b32_e32 v50, 16, v50
	v_lshrrev_b32_e32 v51, 16, v51
	v_and_or_b32 v45, v45, s45, v51
	v_and_or_b32 v44, v44, s45, v50
	v_and_or_b32 v43, v43, s45, v53
	v_and_or_b32 v42, v42, s45, v52
	v_lshl_add_u64 v[50:51], v[94:95], 1, s[76:77]
	global_store_dwordx4 v[50:51], v[42:45], off sc1
	s_or_b64 exec, exec, s[8:9]
	s_and_saveexec_b64 s[8:9], s[36:37]
	s_cbranch_execz .LBB0_281
; #define GAS __attribute__((address_space(1)))
; __device__ __forceinline__ unsigned pk2(float lo, float hi) { return f2bf(lo) | (f2bf(hi) << 16); }
; __device__ __forceinline__ float bfl(unsigned w) { return __uint_as_float(w << 16); }
; __device__ __forceinline__ float bfh(unsigned w) { return __uint_as_float(w & 0xffff0000u); }
; __device__ __forceinline__ void conv_pass(const bf16* Vb, const bf16* Gb, const float* cw  , bf16* Y, int gtid, int nthreads) {
;     ...
;         for (int k = 0; k < NRC; ++k) { if (row + k * rstep < M) { v4u o;
; #pragma unroll
;             for (int q = 0; q < 4; ++q) {
;                 const float ylo = bfl(gg[k][q]) * (w0[2 * q] * bfl(c0[k][q]) + w1[2 * q] * bfl(c1[k][q]) + w2[2 * q] * bfl(c2[k][q]));
;                 const float yhi = bfh(gg[k][q]) * (w0[2 * q + 1] * bfh(c0[k][q]) + w1[2 * q + 1] * bfh(c1[k][q]) + w2[2 * q + 1] * bfh(c2[k][q]));
;                 o[q] = pk2(ylo, yhi);
;             }
;             *(GAS v4u*)(Y + off[k]) = o; } }
.LBB0_283:
	s_waitcnt vmcnt(4)
	v_lshlrev_b32_e32 v51, 16, v35
	v_lshlrev_b32_e32 v50, 16, v34
	v_lshlrev_b32_e32 v45, 16, v39
	v_lshlrev_b32_e32 v44, 16, v38
	v_pk_mul_f32 v[50:51], v[86:87], v[50:51]
	v_and_b32_e32 v35, 0xffff0000, v35
	v_and_b32_e32 v34, 0xffff0000, v34
	v_pk_fma_f32 v[44:45], v[6:7], v[44:45], v[50:51]
	v_lshlrev_b32_e32 v51, 16, v31
	v_lshlrev_b32_e32 v50, 16, v30
	v_and_b32_e32 v39, 0xffff0000, v39
	v_and_b32_e32 v38, 0xffff0000, v38
	v_pk_mul_f32 v[34:35], v[2:3], v[34:35]
	s_waitcnt vmcnt(3)
	v_lshlrev_b32_e32 v43, 16, v59
	v_lshlrev_b32_e32 v42, 16, v58
	v_pk_fma_f32 v[44:45], v[8:9], v[50:51], v[44:45]
	v_pk_fma_f32 v[34:35], v[84:85], v[38:39], v[34:35]
	v_and_b32_e32 v31, 0xffff0000, v31
	v_and_b32_e32 v30, 0xffff0000, v30
	v_pk_mul_f32 v[42:43], v[44:45], v[42:43]
	v_and_b32_e32 v45, 0xffff0000, v59
	v_and_b32_e32 v44, 0xffff0000, v58
	v_pk_fma_f32 v[30:31], v[82:83], v[30:31], v[34:35]
	v_lshlrev_b32_e32 v39, 16, v41
	v_pk_mul_f32 v[30:31], v[30:31], v[44:45]
	v_lshlrev_b32_e32 v45, 16, v37
	v_lshlrev_b32_e32 v44, 16, v36
	v_lshlrev_b32_e32 v38, 16, v40
	v_pk_mul_f32 v[44:45], v[90:91], v[44:45]
	v_and_b32_e32 v37, 0xffff0000, v37
	v_and_b32_e32 v36, 0xffff0000, v36
	v_pk_fma_f32 v[38:39], v[14:15], v[38:39], v[44:45]
	v_lshlrev_b32_e32 v45, 16, v33
	v_lshlrev_b32_e32 v44, 16, v32
	v_and_b32_e32 v41, 0xffff0000, v41
	v_and_b32_e32 v40, 0xffff0000, v40
	v_pk_mul_f32 v[36:37], v[10:11], v[36:37]
	v_lshlrev_b32_e32 v35, 16, v61
	v_lshlrev_b32_e32 v34, 16, v60
	v_pk_fma_f32 v[38:39], v[16:17], v[44:45], v[38:39]
	v_pk_fma_f32 v[36:37], v[88:89], v[40:41], v[36:37]
	v_and_b32_e32 v33, 0xffff0000, v33
	v_and_b32_e32 v32, 0xffff0000, v32
	v_pk_mul_f32 v[34:35], v[38:39], v[34:35]
	v_and_b32_e32 v39, 0xffff0000, v61
	v_and_b32_e32 v38, 0xffff0000, v60
	v_pk_fma_f32 v[32:33], v[4:5], v[32:33], v[36:37]
	s_nop 0
	v_pk_mul_f32 v[32:33], v[32:33], v[38:39]
	v_bfe_u32 v38, v31, 16, 1
	v_bfe_u32 v36, v33, 16, 1
	v_bfe_u32 v37, v32, 16, 1
	v_bfe_u32 v39, v30, 16, 1
	v_add3_u32 v30, v30, v39, s44
	v_add3_u32 v31, v31, v38, s44
	v_add3_u32 v32, v32, v37, s44
	v_add3_u32 v33, v33, v36, s44
	v_bfe_u32 v36, v42, 16, 1
	v_bfe_u32 v37, v43, 16, 1
	v_bfe_u32 v38, v34, 16, 1
	v_bfe_u32 v39, v35, 16, 1
	v_add3_u32 v35, v35, v39, s44
	v_add3_u32 v34, v34, v38, s44
	v_add3_u32 v37, v43, v37, s44
	v_add3_u32 v36, v42, v36, s44
	v_lshrrev_b32_e32 v36, 16, v36
	v_lshrrev_b32_e32 v37, 16, v37
	v_lshrrev_b32_e32 v34, 16, v34
	v_lshrrev_b32_e32 v35, 16, v35
	v_and_or_b32 v33, v33, s45, v35
	v_and_or_b32 v32, v32, s45, v34
	v_and_or_b32 v31, v31, s45, v37
	v_and_or_b32 v30, v30, s45, v36
	v_lshl_add_u64 v[34:35], v[92:93], 1, s[76:77]
	global_store_dwordx4 v[34:35], v[30:33], off sc1
	s_or_b64 exec, exec, s[8:9]
	s_and_saveexec_b64 s[8:9], vcc
	s_cbranch_execz .LBB0_262
.LBB0_284:
	s_waitcnt vmcnt(2)
	v_lshlrev_b32_e32 v33, 16, v27
	v_lshlrev_b32_e32 v32, 16, v26
	v_pk_mul_f32 v[32:33], v[6:7], v[32:33]
	v_lshlrev_b32_e32 v35, 16, v23
	v_lshlrev_b32_e32 v34, 16, v22
	v_and_b32_e32 v27, 0xffff0000, v27
	v_and_b32_e32 v26, 0xffff0000, v26
	v_pk_fma_f32 v[32:33], v[86:87], v[34:35], v[32:33]
	v_lshlrev_b32_e32 v35, 16, v19
	v_lshlrev_b32_e32 v34, 16, v18
	v_pk_mul_f32 v[26:27], v[84:85], v[26:27]
	v_and_b32_e32 v23, 0xffff0000, v23
	v_and_b32_e32 v22, 0xffff0000, v22
	s_waitcnt vmcnt(1)
	v_lshlrev_b32_e32 v31, 16, v47
	v_lshlrev_b32_e32 v30, 16, v46
	v_pk_fma_f32 v[32:33], v[8:9], v[34:35], v[32:33]
	v_pk_fma_f32 v[22:23], v[2:3], v[22:23], v[26:27]
	v_and_b32_e32 v19, 0xffff0000, v19
	v_and_b32_e32 v18, 0xffff0000, v18
	v_pk_mul_f32 v[30:31], v[32:33], v[30:31]
	v_and_b32_e32 v33, 0xffff0000, v47
	v_and_b32_e32 v32, 0xffff0000, v46
	v_pk_fma_f32 v[18:19], v[82:83], v[18:19], v[22:23]
	v_lshlrev_b32_e32 v27, 16, v29
	v_lshlrev_b32_e32 v26, 16, v28
	v_pk_mul_f32 v[18:19], v[18:19], v[32:33]
	v_pk_mul_f32 v[26:27], v[14:15], v[26:27]
	v_lshlrev_b32_e32 v33, 16, v25
	v_lshlrev_b32_e32 v32, 16, v24
	v_and_b32_e32 v29, 0xffff0000, v29
	v_and_b32_e32 v28, 0xffff0000, v28
	v_pk_fma_f32 v[26:27], v[90:91], v[32:33], v[26:27]
	v_lshlrev_b32_e32 v33, 16, v21
	v_lshlrev_b32_e32 v32, 16, v20
	v_pk_mul_f32 v[28:29], v[88:89], v[28:29]
	v_and_b32_e32 v25, 0xffff0000, v25
	v_and_b32_e32 v24, 0xffff0000, v24
	v_lshlrev_b32_e32 v23, 16, v49
	v_lshlrev_b32_e32 v22, 16, v48
	v_pk_fma_f32 v[26:27], v[16:17], v[32:33], v[26:27]
	v_pk_fma_f32 v[24:25], v[10:11], v[24:25], v[28:29]
	v_and_b32_e32 v21, 0xffff0000, v21
	v_and_b32_e32 v20, 0xffff0000, v20
	v_pk_mul_f32 v[22:23], v[26:27], v[22:23]
	v_and_b32_e32 v27, 0xffff0000, v49
	v_and_b32_e32 v26, 0xffff0000, v48
	v_pk_fma_f32 v[20:21], v[4:5], v[20:21], v[24:25]
	v_lshl_add_u64 v[12:13], v[12:13], 1, s[76:77]
	v_pk_mul_f32 v[20:21], v[20:21], v[26:27]
	v_bfe_u32 v26, v19, 16, 1
	v_bfe_u32 v24, v21, 16, 1
	v_bfe_u32 v25, v20, 16, 1
	v_bfe_u32 v27, v18, 16, 1
	v_add3_u32 v18, v18, v27, s44
	v_add3_u32 v19, v19, v26, s44
	v_add3_u32 v20, v20, v25, s44
	v_add3_u32 v21, v21, v24, s44
	v_bfe_u32 v24, v30, 16, 1
	v_bfe_u32 v25, v31, 16, 1
	v_bfe_u32 v26, v22, 16, 1
	v_bfe_u32 v27, v23, 16, 1
	v_add3_u32 v23, v23, v27, s44
	v_add3_u32 v22, v22, v26, s44
	v_add3_u32 v25, v31, v25, s44
	v_add3_u32 v24, v30, v24, s44
	v_lshrrev_b32_e32 v24, 16, v24
	v_lshrrev_b32_e32 v25, 16, v25
	v_lshrrev_b32_e32 v22, 16, v22
	v_lshrrev_b32_e32 v23, 16, v23
	v_and_or_b32 v21, v21, s45, v23
	v_and_or_b32 v20, v20, s45, v22
	v_and_or_b32 v19, v19, s45, v25
	v_and_or_b32 v18, v18, s45, v24
	global_store_dwordx4 v[12:13], v[18:21], off sc1
	s_branch .LBB0_262

;     __device__ __forceinline__ void operator()(const f32x4 (&acc)[2][2][4][2], const Unit& u, int wr, int wc, int fr, int fq) const {
;         const int col0 = u.pn * BM + wc * 32 + 4 * fq;
; #pragma unroll
;         for (int ai = 0; ai < 2; ++ai) {
;             const size_t off0 = (size_t)(u.pm * BM + ai * HALF + wr * 64 + fr) * ldc + col0;
;             f32x4 pre[4][2][2];
; #pragma unroll
;             for (int m = 0; m < 4; ++m)
; #pragma unroll
;                 for (int bj = 0; bj < 2; ++bj)
; #pragma unroll
;                     for (int n = 0; n < 2; ++n) pre[m][bj][n] = *(const f32x4*)(base + off0 + (size_t)(m * 16) * ldc + bj * HALF + n * 16);
; #pragma unroll
;             for (int m = 0; m < 4; ++m)
; #pragma unroll
;                 for (int bj = 0; bj < 2; ++bj)
; #pragma unroll
;                     for (int n = 0; n < 2; ++n) *(f32x4*)(out + off0 + (size_t)(m * 16) * ldc + bj * HALF + n * 16) = pre[m][bj][n] + acc[ai][bj][m][n];
;             asm volatile("" ::: "memory");
;         }
.LBB0_354:
	v_lshl_add_u32 v150, s23, 8, v152
	v_lshl_or_b32 v148, s22, 8, v154
	v_ashrrev_i32_e32 v151, 31, v150
	v_ashrrev_i32_e32 v149, 31, v148
	v_lshlrev_b64 v[130:131], 10, v[150:151]
	v_lshl_add_u64 v[130:131], v[130:131], 0, v[148:149]
	v_lshlrev_b64 v[196:197], 2, v[130:131]
	v_lshl_add_u64 v[130:131], s[6:7], 0, v[196:197]
	v_add_co_u32_e32 v132, vcc, 0x10000, v130
	global_load_dwordx4 v[156:159], v[130:131], off
	global_load_dwordx4 v[160:163], v[130:131], off offset:64
	global_load_dwordx4 v[164:167], v[130:131], off offset:512
	global_load_dwordx4 v[168:171], v[130:131], off offset:576
	v_addc_co_u32_e32 v133, vcc, 0, v131, vcc
	global_load_dwordx4 v[172:175], v[132:133], off
	global_load_dwordx4 v[176:179], v[132:133], off offset:64
	global_load_dwordx4 v[180:183], v[132:133], off offset:512
	global_load_dwordx4 v[184:187], v[132:133], off offset:576
	v_add_co_u32_e32 v132, vcc, 0x20000, v130
	s_mov_b64 s[8:9], -1
	s_nop 0
	v_addc_co_u32_e32 v133, vcc, 0, v131, vcc
	v_add_co_u32_e32 v130, vcc, 0x30000, v130
	global_load_dwordx4 v[188:191], v[132:133], off
	global_load_dwordx4 v[192:195], v[132:133], off offset:64
	global_load_dwordx4 v[206:209], v[132:133], off offset:512
	global_load_dwordx4 v[210:213], v[132:133], off offset:576
	v_addc_co_u32_e32 v131, vcc, 0, v131, vcc
	global_load_dwordx4 v[214:217], v[130:131], off
	global_load_dwordx4 v[138:141], v[130:131], off offset:64
	global_load_dwordx4 v[134:137], v[130:131], off offset:512
	s_nop 0
	global_load_dwordx4 v[130:133], v[130:131], off offset:576
	s_waitcnt vmcnt(0)
	v_pk_add_f32 v[156:157], v[126:127], v[156:157]
	v_lshl_add_u64 v[126:127], s[68:69], 0, v[196:197]
	v_pk_add_f32 v[116:117], v[116:117], v[166:167]
	v_pk_add_f32 v[114:115], v[114:115], v[164:165]
	global_store_dwordx4 v[126:127], v[114:117], off offset:512 sc1
	v_pk_add_f32 v[100:101], v[100:101], v[182:183]
	v_pk_add_f32 v[98:99], v[98:99], v[180:181]
	v_add_co_u32_e32 v114, vcc, s54, v126
	v_pk_add_f32 v[112:113], v[112:113], v[170:171]
	s_nop 0
	v_addc_co_u32_e32 v115, vcc, 0, v127, vcc
	global_store_dwordx4 v[114:115], v[98:101], off offset:512 sc1
	v_pk_add_f32 v[84:85], v[84:85], v[208:209]
	v_pk_add_f32 v[82:83], v[82:83], v[206:207]
	v_add_co_u32_e32 v98, vcc, s59, v126
	v_pk_add_f32 v[68:69], v[68:69], v[132:133]
	s_nop 0
	v_addc_co_u32_e32 v99, vcc, 0, v127, vcc
	global_store_dwordx4 v[98:99], v[82:85], off offset:512 sc1
	v_pk_add_f32 v[66:67], v[66:67], v[130:131]
	v_pk_add_f32 v[110:111], v[110:111], v[168:169]
	v_add_co_u32_e32 v82, vcc, s56, v126
	v_pk_add_f32 v[96:97], v[96:97], v[186:187]
	s_nop 0
	v_addc_co_u32_e32 v83, vcc, 0, v127, vcc
	global_store_dwordx4 v[82:83], v[66:69], off offset:576 sc1
	v_pk_add_f32 v[94:95], v[94:95], v[184:185]
	v_pk_add_f32 v[80:81], v[80:81], v[212:213]
	v_add_u32_e32 v66, 0x80, v150
	v_ashrrev_i32_e32 v67, 31, v66
	v_lshlrev_b64 v[66:67], 10, v[66:67]
	v_pk_add_f32 v[78:79], v[78:79], v[210:211]
	v_lshl_add_u64 v[66:67], v[66:67], 0, v[148:149]
	v_pk_add_f32 v[158:159], v[128:129], v[158:159]
	v_pk_add_f32 v[124:125], v[124:125], v[162:163]
	v_pk_add_f32 v[122:123], v[122:123], v[160:161]
	global_store_dwordx4 v[126:127], v[110:113], off offset:576 sc1
	v_pk_add_f32 v[108:109], v[108:109], v[178:179]
	v_pk_add_f32 v[106:107], v[106:107], v[176:177]
	v_pk_add_f32 v[112:113], v[120:121], v[174:175]
	v_pk_add_f32 v[110:111], v[118:119], v[172:173]
	global_store_dwordx4 v[114:115], v[94:97], off offset:576 sc1
	v_pk_add_f32 v[92:93], v[92:93], v[194:195]
	v_pk_add_f32 v[90:91], v[90:91], v[192:193]
	v_pk_add_f32 v[96:97], v[104:105], v[190:191]
	v_pk_add_f32 v[94:95], v[102:103], v[188:189]
	global_store_dwordx4 v[98:99], v[78:81], off offset:576 sc1
	v_pk_add_f32 v[76:77], v[76:77], v[140:141]
	v_pk_add_f32 v[74:75], v[74:75], v[138:139]
	v_pk_add_f32 v[80:81], v[88:89], v[216:217]
	v_pk_add_f32 v[78:79], v[86:87], v[214:215]
	v_pk_add_f32 v[72:73], v[72:73], v[136:137]
	v_pk_add_f32 v[70:71], v[70:71], v[134:135]
	v_lshlrev_b64 v[130:131], 2, v[66:67]
	global_store_dwordx4 v[126:127], v[156:159], off sc1
	global_store_dwordx4 v[126:127], v[122:125], off offset:64 sc1
	global_store_dwordx4 v[114:115], v[110:113], off sc1
	global_store_dwordx4 v[114:115], v[106:109], off offset:64 sc1
	global_store_dwordx4 v[98:99], v[94:97], off sc1
	global_store_dwordx4 v[98:99], v[90:93], off offset:64 sc1
	global_store_dwordx4 v[82:83], v[78:81], off sc1
	global_store_dwordx4 v[82:83], v[74:77], off offset:64 sc1
	global_store_dwordx4 v[82:83], v[70:73], off offset:512 sc1
	v_lshl_add_u64 v[66:67], s[6:7], 0, v[130:131]
	v_add_co_u32_e32 v68, vcc, s54, v66
	global_load_dwordx4 v[94:97], v[66:67], off
	global_load_dwordx4 v[98:101], v[66:67], off offset:64
	global_load_dwordx4 v[102:105], v[66:67], off offset:512
	global_load_dwordx4 v[106:109], v[66:67], off offset:576
	v_addc_co_u32_e32 v69, vcc, 0, v67, vcc
	global_load_dwordx4 v[110:113], v[68:69], off
	global_load_dwordx4 v[114:117], v[68:69], off offset:64
	global_load_dwordx4 v[118:121], v[68:69], off offset:512
	global_load_dwordx4 v[122:125], v[68:69], off offset:576
	v_add_co_u32_e32 v68, vcc, s59, v66
	s_waitcnt vmcnt(7)
;     __device__ __forceinline__ void operator()(const f32x4 (&acc)[2][2][4][2], const Unit& u, int wr, int wc, int fr, int fq) const {
;     ...
;                     for (int n = 0; n < 2; ++n) pre[m][bj][n] = *(const f32x4*)(base + off0 + (size_t)(m * 16) * ldc + bj * HALF + n * 16);
; #pragma unroll
;             for (int m = 0; m < 4; ++m)
; #pragma unroll
;                 for (int bj = 0; bj < 2; ++bj)
; #pragma unroll
;                     for (int n = 0; n < 2; ++n) *(f32x4*)(out + off0 + (size_t)(m * 16) * ldc + bj * HALF + n * 16) = pre[m][bj][n] + acc[ai][bj][m][n];
;             asm volatile("" ::: "memory");
;         }
	v_pk_add_f32 v[94:95], v[62:63], v[94:95]
	v_addc_co_u32_e32 v69, vcc, 0, v67, vcc
	global_load_dwordx4 v[126:129], v[68:69], off
	global_load_dwordx4 v[90:93], v[68:69], off offset:64
	global_load_dwordx4 v[86:89], v[68:69], off offset:512
	global_load_dwordx4 v[82:85], v[68:69], off offset:576
	v_add_co_u32_e32 v66, vcc, s56, v66
	v_lshl_add_u64 v[62:63], s[68:69], 0, v[130:131]
	s_nop 0
	v_addc_co_u32_e32 v67, vcc, 0, v67, vcc
	global_load_dwordx4 v[78:81], v[66:67], off
	global_load_dwordx4 v[74:77], v[66:67], off offset:64
	global_load_dwordx4 v[70:73], v[66:67], off offset:512
	s_nop 0
	global_load_dwordx4 v[66:69], v[66:67], off offset:576
	s_waitcnt vmcnt(13)
	v_pk_add_f32 v[52:53], v[52:53], v[104:105]
	v_pk_add_f32 v[50:51], v[50:51], v[102:103]
	global_store_dwordx4 v[62:63], v[50:53], off offset:512 sc1
	s_waitcnt vmcnt(10)
	v_pk_add_f32 v[36:37], v[36:37], v[120:121]
	v_pk_add_f32 v[34:35], v[34:35], v[118:119]
	v_add_co_u32_e32 v50, vcc, s54, v62
	v_pk_add_f32 v[48:49], v[48:49], v[108:109]
	s_nop 0
	v_addc_co_u32_e32 v51, vcc, 0, v63, vcc
	global_store_dwordx4 v[50:51], v[34:37], off offset:512 sc1
	v_pk_add_f32 v[46:47], v[46:47], v[106:107]
	s_waitcnt vmcnt(10)
	v_pk_add_f32 v[32:33], v[32:33], v[124:125]
	v_add_co_u32_e32 v34, vcc, s59, v62
	v_pk_add_f32 v[30:31], v[30:31], v[122:123]
	s_nop 0
	v_addc_co_u32_e32 v35, vcc, 0, v63, vcc
	v_pk_add_f32 v[96:97], v[64:65], v[96:97]
	v_pk_add_f32 v[60:61], v[60:61], v[100:101]
	v_pk_add_f32 v[58:59], v[58:59], v[98:99]
	global_store_dwordx4 v[62:63], v[46:49], off offset:576 sc1
	v_pk_add_f32 v[44:45], v[44:45], v[116:117]
	v_pk_add_f32 v[42:43], v[42:43], v[114:115]
	v_pk_add_f32 v[48:49], v[56:57], v[112:113]
	v_pk_add_f32 v[46:47], v[54:55], v[110:111]
	global_store_dwordx4 v[50:51], v[30:33], off offset:576 sc1
	global_store_dwordx4 v[62:63], v[94:97], off sc1
	global_store_dwordx4 v[62:63], v[58:61], off offset:64 sc1
	global_store_dwordx4 v[50:51], v[46:49], off sc1
	global_store_dwordx4 v[50:51], v[42:45], off offset:64 sc1
	s_waitcnt vmcnt(15)
	v_pk_add_f32 v[32:33], v[40:41], v[128:129]
	v_pk_add_f32 v[30:31], v[38:39], v[126:127]
	s_waitcnt vmcnt(14)
	v_pk_add_f32 v[28:29], v[28:29], v[92:93]
	s_waitcnt vmcnt(12)
	v_pk_add_f32 v[16:17], v[16:17], v[84:85]
	v_pk_add_f32 v[14:15], v[14:15], v[82:83]
	global_store_dwordx4 v[34:35], v[14:17], off offset:576 sc1
	v_pk_add_f32 v[26:27], v[26:27], v[90:91]
	v_pk_add_f32 v[24:25], v[24:25], v[88:89]
	s_waitcnt vmcnt(12)
	v_pk_add_f32 v[14:15], v[18:19], v[78:79]
	v_add_co_u32_e32 v18, vcc, s56, v62
	v_pk_add_f32 v[22:23], v[22:23], v[86:87]
	v_pk_add_f32 v[16:17], v[20:21], v[80:81]
	v_addc_co_u32_e32 v19, vcc, 0, v63, vcc
	s_waitcnt vmcnt(11)
	v_pk_add_f32 v[12:13], v[12:13], v[76:77]
	v_pk_add_f32 v[10:11], v[10:11], v[74:75]
	s_waitcnt vmcnt(10)
	v_pk_add_f32 v[8:9], v[8:9], v[72:73]
	v_pk_add_f32 v[6:7], v[6:7], v[70:71]
	s_waitcnt vmcnt(9)
	v_pk_add_f32 v[4:5], v[4:5], v[68:69]
	v_pk_add_f32 v[2:3], v[2:3], v[66:67]
	global_store_dwordx4 v[34:35], v[30:33], off sc1
	global_store_dwordx4 v[34:35], v[26:29], off offset:64 sc1
	global_store_dwordx4 v[34:35], v[22:25], off offset:512 sc1
	global_store_dwordx4 v[18:19], v[14:17], off sc1
	global_store_dwordx4 v[18:19], v[10:13], off offset:64 sc1
	global_store_dwordx4 v[18:19], v[6:9], off offset:512 sc1
	global_store_dwordx4 v[18:19], v[2:5], off offset:576 sc1
	s_andn2_b64 vcc, exec, s[36:37]
	s_cbranch_vccnz .LBB0_343
	s_andn2_b64 vcc, exec, s[4:5]
	s_cbranch_vccnz .LBB0_342
	s_barrier
	s_branch .LBB0_342

; #define GAS __attribute__((address_space(1)))
; __device__ __forceinline__ float wave_sum(float v) { return wave_sum64(v); }
; __device__ __forceinline__ void rms_rows_f32_inplace(float* X, const float* g, int gw, int NGW, int) {
;     ...
;     for (int m = gw; m < M; m += NR * NGW) {
;         f32x4 v[NR][4]; float s[NR];
; #pragma unroll
;         for (int k = 0; k < NR; ++k) { const int mk = (m + k * NGW < M) ? m + k * NGW : m; const GAS f32x4* xr = (const GAS f32x4*)(X + (size_t)mk * D) + lane;
; #pragma unroll
;             for (int j = 0; j < 4; ++j) v[k][j] = xr[64 * j]; }
; #pragma unroll
;         for (int k = 0; k < NR; ++k) { float a = 0.f;
; #pragma unroll
;             for (int j = 0; j < 4; ++j) a += (v[k][j].x * v[k][j].x + v[k][j].y * v[k][j].y) + (v[k][j].z * v[k][j].z + v[k][j].w * v[k][j].w);
;             s[k] = __builtin_amdgcn_rsqf(wave_sum(a) * (1.f / D) + RMS_EPS); }
.LBB0_412:
	s_ashr_i32 s13, s12, 31
	s_lshl_b64 s[0:1], s[12:13], 12
	s_waitcnt vmcnt(4)
	v_lshl_add_u64 v[82:83], v[80:81], 0, s[0:1]
	s_add_i32 s0, s12, s33
	s_cmp_lt_i32 s0, 0x8000
	global_load_dwordx4 v[76:79], v[82:83], off
	global_load_dwordx4 v[72:75], v[82:83], off offset:1024
	global_load_dwordx4 v[68:71], v[82:83], off offset:2048
	global_load_dwordx4 v[60:63], v[82:83], off offset:3072
	s_cselect_b32 s2, s0, s12
	s_ashr_i32 s3, s2, 31
	s_lshl_b64 s[2:3], s[2:3], 12
	v_lshl_add_u64 v[16:17], v[80:81], 0, s[2:3]
	global_load_dwordx4 v[64:67], v[16:17], off
	global_load_dwordx4 v[56:59], v[16:17], off offset:1024
	global_load_dwordx4 v[52:55], v[16:17], off offset:2048
	global_load_dwordx4 v[48:51], v[16:17], off offset:3072
	s_add_i32 s6, s97, s12
	s_cmp_lt_i32 s6, 0x8000
	s_cselect_b64 s[8:9], -1, 0
	s_and_b64 s[2:3], s[8:9], exec
	s_cselect_b32 s2, s6, s12
	s_ashr_i32 s3, s2, 31
	s_lshl_b64 s[2:3], s[2:3], 12
	v_lshl_add_u64 v[16:17], v[80:81], 0, s[2:3]
	global_load_dwordx4 v[44:47], v[16:17], off
	global_load_dwordx4 v[40:43], v[16:17], off offset:1024
	global_load_dwordx4 v[36:39], v[16:17], off offset:2048
	s_add_i32 s2, s14, s12
	s_cmp_lt_i32 s2, 0x8000
	s_cselect_b64 s[4:5], -1, 0
	global_load_dwordx4 v[32:35], v[16:17], off offset:3072
	s_and_b64 s[10:11], s[4:5], exec
	s_cselect_b32 s10, s2, s12
	s_ashr_i32 s11, s10, 31
	s_lshl_b64 s[10:11], s[10:11], 12
	v_lshl_add_u64 v[86:87], v[80:81], 0, s[10:11]
	global_load_dwordx4 v[28:31], v[86:87], off
	global_load_dwordx4 v[24:27], v[86:87], off offset:1024
	global_load_dwordx4 v[20:23], v[86:87], off offset:2048
	global_load_dwordx4 v[16:19], v[86:87], off offset:3072
	s_cmpk_gt_i32 s0, 0x7fff
	s_waitcnt vmcnt(15)
	v_mul_f32_e32 v85, v77, v77
	v_mul_f32_e32 v86, v79, v79
	s_waitcnt vmcnt(14)
	v_mul_f32_e32 v87, v73, v73
	v_mul_f32_e32 v88, v75, v75
	s_waitcnt vmcnt(13)
	v_mul_f32_e32 v89, v69, v69
	v_mul_f32_e32 v90, v71, v71
	v_fmac_f32_e32 v85, v76, v76
	v_fmac_f32_e32 v86, v78, v78
	v_fmac_f32_e32 v87, v72, v72
	v_fmac_f32_e32 v88, v74, v74
	s_waitcnt vmcnt(12)
	v_mul_f32_e32 v91, v61, v61
	v_mul_f32_e32 v92, v63, v63
	v_fmac_f32_e32 v89, v68, v68
	v_fmac_f32_e32 v90, v70, v70
	v_add_f32_e32 v85, v85, v86
	v_add_f32_e32 v86, v87, v88
	v_fmac_f32_e32 v91, v60, v60
	v_fmac_f32_e32 v92, v62, v62
	v_add_f32_e32 v87, v89, v90
	v_add_f32_e32 v85, v85, v86
	v_add_f32_e32 v88, v91, v92
	v_add_f32_e32 v85, v85, v87
	s_waitcnt vmcnt(11)
	v_mul_f32_e32 v86, v65, v65
	v_mul_f32_e32 v87, v67, v67
	s_waitcnt vmcnt(10)
	v_mul_f32_e32 v89, v57, v57
	v_mul_f32_e32 v90, v59, v59
	v_add_f32_e32 v85, v85, v88
	v_fmac_f32_e32 v86, v64, v64
	v_fmac_f32_e32 v87, v66, v66
	v_fmac_f32_e32 v89, v56, v56
	v_fmac_f32_e32 v90, v58, v58
	v_add_f32_e32 v86, v86, v87
	v_add_f32_e32 v87, v89, v90
	ds_swizzle_b32 v89, v85 offset:swizzle(SWAP,1)
	s_waitcnt vmcnt(9)
	v_mul_f32_e32 v91, v53, v53
	v_mul_f32_e32 v92, v55, v55
	s_waitcnt vmcnt(8)
	v_mul_f32_e32 v93, v49, v49
	v_mul_f32_e32 v94, v51, v51
	s_waitcnt lgkmcnt(0)
	v_add_f32_e32 v85, v85, v89
	ds_swizzle_b32 v89, v85 offset:swizzle(SWAP,2)
	v_fmac_f32_e32 v91, v52, v52
	v_fmac_f32_e32 v92, v54, v54
	v_fmac_f32_e32 v93, v48, v48
	v_fmac_f32_e32 v94, v50, v50
	s_waitcnt lgkmcnt(0)
	v_add_f32_e32 v85, v85, v89
	ds_swizzle_b32 v89, v85 offset:swizzle(SWAP,4)
	v_add_f32_e32 v88, v91, v92
	v_add_f32_e32 v86, v86, v87
	v_add_f32_e32 v90, v93, v94
	v_add_f32_e32 v86, v86, v88
	v_add_f32_e32 v86, v86, v90
	s_waitcnt vmcnt(7)
	v_mul_f32_e32 v88, v45, v45
	v_mul_f32_e32 v90, v47, v47
	s_waitcnt vmcnt(6)
	v_mul_f32_e32 v91, v41, v41
	v_mul_f32_e32 v92, v43, v43
	v_fmac_f32_e32 v88, v44, v44
	v_fmac_f32_e32 v90, v46, v46
	v_fmac_f32_e32 v91, v40, v40
	v_fmac_f32_e32 v92, v42, v42
	s_waitcnt lgkmcnt(0)
	v_add_f32_e32 v85, v85, v89
	ds_swizzle_b32 v89, v85 offset:swizzle(SWAP,8)
	v_add_f32_e32 v88, v88, v90
	v_add_f32_e32 v90, v91, v92
	ds_swizzle_b32 v87, v86 offset:swizzle(SWAP,1)
	s_waitcnt vmcnt(5)
	v_mul_f32_e32 v93, v37, v37
	v_add_f32_e32 v88, v88, v90
	v_mul_f32_e32 v90, v39, v39
	v_fmac_f32_e32 v93, v36, v36
	v_fmac_f32_e32 v90, v38, v38
	v_add_f32_e32 v90, v93, v90
	v_add_f32_e32 v88, v88, v90
	s_waitcnt vmcnt(4)
; #define GAS __attribute__((address_space(1)))
; __device__ __forceinline__ float wave_sum(float v) { return wave_sum64(v); }
; __device__ __forceinline__ void rms_rows_f32_inplace(float* X, const float* g, int gw, int NGW, int) {
;     ...
;         for (int k = 0; k < NR; ++k) { float a = 0.f;
; #pragma unroll
;             for (int j = 0; j < 4; ++j) a += (v[k][j].x * v[k][j].x + v[k][j].y * v[k][j].y) + (v[k][j].z * v[k][j].z + v[k][j].w * v[k][j].w);
;             s[k] = __builtin_amdgcn_rsqf(wave_sum(a) * (1.f / D) + RMS_EPS); }
; #pragma unroll
;         for (int k = 0; k < NR; ++k) if (m + k * NGW < M) { GAS f32x4* xr = (GAS f32x4*)(X + (size_t)(m + k * NGW) * D) + lane;
; #pragma unroll
;             for (int j = 0; j < 4; ++j) xr[64 * j] = v[k][j] * s[k] * gv[j]; }
;     }
	v_mul_f32_e32 v90, v33, v33
	v_mul_f32_e32 v91, v35, v35
	s_waitcnt lgkmcnt(1)
	v_add_f32_e32 v85, v85, v89
	v_fmac_f32_e32 v90, v32, v32
	v_fmac_f32_e32 v91, v34, v34
	s_waitcnt lgkmcnt(0)
	v_add_f32_e32 v86, v86, v87
	ds_swizzle_b32 v89, v85 offset:swizzle(SWAP,16)
	v_add_f32_e32 v90, v90, v91
	ds_swizzle_b32 v87, v86 offset:swizzle(SWAP,2)
	v_add_f32_e32 v88, v88, v90
	s_waitcnt vmcnt(3)
	v_mul_f32_e32 v90, v29, v29
	v_mul_f32_e32 v91, v31, v31
	v_fmac_f32_e32 v90, v28, v28
	v_fmac_f32_e32 v91, v30, v30
	v_add_f32_e32 v90, v90, v91
	s_waitcnt vmcnt(2)
	v_mul_f32_e32 v91, v25, v25
	v_mul_f32_e32 v92, v27, v27
	v_fmac_f32_e32 v91, v24, v24
	v_fmac_f32_e32 v92, v26, v26
	s_waitcnt lgkmcnt(1)
	v_add_f32_e32 v85, v85, v89
	v_add_f32_e32 v91, v91, v92
	s_waitcnt lgkmcnt(0)
	v_add_f32_e32 v86, v86, v87
	v_mov_b32_e32 v89, v85
	v_add_f32_e32 v90, v90, v91
	s_waitcnt vmcnt(1)
	v_mul_f32_e32 v91, v21, v21
	v_mul_f32_e32 v92, v23, v23
	ds_swizzle_b32 v87, v86 offset:swizzle(SWAP,4)
	v_permlane32_swap_b32_e32 v85, v89
	v_fmac_f32_e32 v91, v20, v20
	v_fmac_f32_e32 v92, v22, v22
	v_add_f32_e32 v85, v85, v89
	v_add_f32_e32 v89, v91, v92
	v_add_f32_e32 v89, v90, v89
	s_waitcnt vmcnt(0)
	v_mul_f32_e32 v90, v17, v17
	v_mul_f32_e32 v91, v19, v19
	v_fmac_f32_e32 v90, v16, v16
	v_fmac_f32_e32 v91, v18, v18
	v_add_f32_e32 v90, v90, v91
	s_waitcnt lgkmcnt(0)
	v_add_f32_e32 v86, v86, v87
	v_add_f32_e32 v89, v89, v90
	ds_swizzle_b32 v87, v86 offset:swizzle(SWAP,8)
	ds_swizzle_b32 v92, v88 offset:swizzle(SWAP,1)
	ds_swizzle_b32 v90, v89 offset:swizzle(SWAP,1)
	v_fmamk_f32 v85, v85, 0x3a800000, v84
	s_waitcnt lgkmcnt(2)
	v_add_f32_e32 v86, v86, v87
	s_waitcnt lgkmcnt(1)
	v_add_f32_e32 v88, v88, v92
	s_waitcnt lgkmcnt(0)
	v_add_f32_e32 v89, v89, v90
	ds_swizzle_b32 v87, v86 offset:swizzle(SWAP,16)
	ds_swizzle_b32 v91, v88 offset:swizzle(SWAP,2)
	ds_swizzle_b32 v90, v89 offset:swizzle(SWAP,2)
	v_rsq_f32_e32 v92, v85
	s_waitcnt lgkmcnt(2)
	v_add_f32_e32 v85, v86, v87
	s_waitcnt lgkmcnt(1)
	v_add_f32_e32 v88, v88, v91
	s_waitcnt lgkmcnt(0)
	v_add_f32_e32 v86, v89, v90
	ds_swizzle_b32 v91, v88 offset:swizzle(SWAP,4)
	ds_swizzle_b32 v87, v86 offset:swizzle(SWAP,4)
	v_pk_mul_f32 v[78:79], v[78:79], v[92:93] op_sel_hi:[1,0]
	v_pk_mul_f32 v[76:77], v[76:77], v[92:93] op_sel_hi:[1,0]
	v_pk_mul_f32 v[72:73], v[72:73], v[92:93] op_sel_hi:[1,0]
	s_waitcnt lgkmcnt(1)
	v_add_f32_e32 v88, v88, v91
	v_pk_mul_f32 v[90:91], v[2:3], v[78:79]
	s_waitcnt lgkmcnt(0)
	v_add_f32_e32 v78, v86, v87
	ds_swizzle_b32 v89, v88 offset:swizzle(SWAP,8)
	ds_swizzle_b32 v79, v78 offset:swizzle(SWAP,8)
	v_pk_mul_f32 v[74:75], v[74:75], v[92:93] op_sel_hi:[1,0]
	v_pk_mul_f32 v[68:69], v[68:69], v[92:93] op_sel_hi:[1,0]
	v_pk_mul_f32 v[70:71], v[70:71], v[92:93] op_sel_hi:[1,0]
	s_waitcnt lgkmcnt(1)
	v_add_f32_e32 v86, v88, v89
	v_pk_mul_f32 v[88:89], v[0:1], v[76:77]
	s_waitcnt lgkmcnt(0)
	v_add_f32_e32 v76, v78, v79
	ds_swizzle_b32 v87, v86 offset:swizzle(SWAP,16)
	ds_swizzle_b32 v77, v76 offset:swizzle(SWAP,16)
	v_pk_mul_f32 v[60:61], v[60:61], v[92:93] op_sel_hi:[1,0]
	v_pk_mul_f32 v[62:63], v[62:63], v[92:93] op_sel_hi:[1,0]
	v_pk_mul_f32 v[74:75], v[6:7], v[74:75]
	s_waitcnt lgkmcnt(1)
	v_add_f32_e32 v78, v86, v87
	s_waitcnt lgkmcnt(0)
	v_add_f32_e32 v76, v76, v77
	v_mov_b32_e32 v86, v85
	v_mov_b32_e32 v79, v78
	v_mov_b32_e32 v77, v76
	v_permlane32_swap_b32_e32 v85, v86
	v_permlane32_swap_b32_e32 v78, v79
	v_permlane32_swap_b32_e32 v76, v77
	v_pk_mul_f32 v[72:73], v[4:5], v[72:73]
	v_pk_mul_f32 v[70:71], v[10:11], v[70:71]
	v_pk_mul_f32 v[68:69], v[8:9], v[68:69]
	v_pk_mul_f32 v[62:63], v[14:15], v[62:63]
	v_pk_mul_f32 v[60:61], v[12:13], v[60:61]
	global_store_dwordx4 v[82:83], v[88:91], off sc1
	global_store_dwordx4 v[82:83], v[72:75], off offset:1024 sc1
	global_store_dwordx4 v[82:83], v[68:71], off offset:2048 sc1
	global_store_dwordx4 v[82:83], v[60:63], off offset:3072 sc1
	s_cbranch_scc0 .LBB0_415
	s_andn2_b64 vcc, exec, s[8:9]
	s_cbranch_vccz .LBB0_416

; #define GAS __attribute__((address_space(1)))
; __device__ __forceinline__ void rms_rows_f32_inplace(float* X, const float* g, int gw, int NGW, int) {
;     ...
; #pragma unroll
;         for (int k = 0; k < NR; ++k) if (m + k * NGW < M) { GAS f32x4* xr = (GAS f32x4*)(X + (size_t)(m + k * NGW) * D) + lane;
; #pragma unroll
;             for (int j = 0; j < 4; ++j) xr[64 * j] = v[k][j] * s[k] * gv[j]; }
;     }
.LBB0_415:
	s_nop 0
	v_add_f32_e32 v60, v85, v86
	v_fmamk_f32 v60, v60, 0x3a800000, v84
	v_rsq_f32_e32 v68, v60
	s_ashr_i32 s1, s0, 31
	s_lshl_b64 s[10:11], s[0:1], 12
	v_lshl_add_u64 v[70:71], v[80:81], 0, s[10:11]
	v_pk_mul_f32 v[60:61], v[66:67], v[68:69] op_sel_hi:[1,0]
	v_pk_mul_f32 v[64:65], v[64:65], v[68:69] op_sel_hi:[1,0]
	v_pk_mul_f32 v[58:59], v[58:59], v[68:69] op_sel_hi:[1,0]
	v_pk_mul_f32 v[56:57], v[56:57], v[68:69] op_sel_hi:[1,0]
	v_pk_mul_f32 v[54:55], v[54:55], v[68:69] op_sel_hi:[1,0]
	v_pk_mul_f32 v[52:53], v[52:53], v[68:69] op_sel_hi:[1,0]
	v_pk_mul_f32 v[50:51], v[50:51], v[68:69] op_sel_hi:[1,0]
	v_pk_mul_f32 v[48:49], v[48:49], v[68:69] op_sel_hi:[1,0]
	v_pk_mul_f32 v[62:63], v[2:3], v[60:61]
	v_pk_mul_f32 v[60:61], v[0:1], v[64:65]
	v_pk_mul_f32 v[58:59], v[6:7], v[58:59]
	v_pk_mul_f32 v[56:57], v[4:5], v[56:57]
	v_pk_mul_f32 v[54:55], v[10:11], v[54:55]
	v_pk_mul_f32 v[52:53], v[8:9], v[52:53]
	v_pk_mul_f32 v[50:51], v[14:15], v[50:51]
	v_pk_mul_f32 v[48:49], v[12:13], v[48:49]
	global_store_dwordx4 v[70:71], v[60:63], off sc1
	global_store_dwordx4 v[70:71], v[56:59], off offset:1024 sc1
	global_store_dwordx4 v[70:71], v[52:55], off offset:2048 sc1
	global_store_dwordx4 v[70:71], v[48:51], off offset:3072 sc1
	s_andn2_b64 vcc, exec, s[8:9]
	s_cbranch_vccnz .LBB0_414
.LBB0_416:
	v_add_f32_e32 v48, v78, v79
	v_fmamk_f32 v48, v48, 0x3a800000, v84
	v_rsq_f32_e32 v48, v48
	s_ashr_i32 s7, s6, 31
	s_lshl_b64 s[6:7], s[6:7], 12
	v_lshl_add_u64 v[50:51], v[80:81], 0, s[6:7]
	v_pk_mul_f32 v[46:47], v[46:47], v[48:49] op_sel_hi:[1,0]
	v_pk_mul_f32 v[44:45], v[44:45], v[48:49] op_sel_hi:[1,0]
	v_pk_mul_f32 v[42:43], v[42:43], v[48:49] op_sel_hi:[1,0]
	v_pk_mul_f32 v[40:41], v[40:41], v[48:49] op_sel_hi:[1,0]
	v_pk_mul_f32 v[38:39], v[38:39], v[48:49] op_sel_hi:[1,0]
	v_pk_mul_f32 v[36:37], v[36:37], v[48:49] op_sel_hi:[1,0]
	v_pk_mul_f32 v[34:35], v[34:35], v[48:49] op_sel_hi:[1,0]
	v_pk_mul_f32 v[32:33], v[32:33], v[48:49] op_sel_hi:[1,0]
	v_pk_mul_f32 v[46:47], v[2:3], v[46:47]
	v_pk_mul_f32 v[44:45], v[0:1], v[44:45]
	v_pk_mul_f32 v[42:43], v[6:7], v[42:43]
	v_pk_mul_f32 v[40:41], v[4:5], v[40:41]
	v_pk_mul_f32 v[38:39], v[10:11], v[38:39]
	v_pk_mul_f32 v[36:37], v[8:9], v[36:37]
	v_pk_mul_f32 v[34:35], v[14:15], v[34:35]
	v_pk_mul_f32 v[32:33], v[12:13], v[32:33]
	global_store_dwordx4 v[50:51], v[44:47], off sc1
	global_store_dwordx4 v[50:51], v[40:43], off offset:1024 sc1
	global_store_dwordx4 v[50:51], v[36:39], off offset:2048 sc1
	global_store_dwordx4 v[50:51], v[32:35], off offset:3072 sc1
	s_andn2_b64 vcc, exec, s[4:5]
	s_cbranch_vccnz .LBB0_411
.LBB0_417:
	v_add_f32_e32 v32, v76, v77
	v_fmamk_f32 v32, v32, 0x3a800000, v84
	v_rsq_f32_e32 v32, v32
	s_ashr_i32 s3, s2, 31
	s_lshl_b64 s[2:3], s[2:3], 12
	v_lshl_add_u64 v[34:35], v[80:81], 0, s[2:3]
	v_pk_mul_f32 v[30:31], v[30:31], v[32:33] op_sel_hi:[1,0]
	v_pk_mul_f32 v[28:29], v[28:29], v[32:33] op_sel_hi:[1,0]
	v_pk_mul_f32 v[26:27], v[26:27], v[32:33] op_sel_hi:[1,0]
	v_pk_mul_f32 v[24:25], v[24:25], v[32:33] op_sel_hi:[1,0]
	v_pk_mul_f32 v[22:23], v[22:23], v[32:33] op_sel_hi:[1,0]
	v_pk_mul_f32 v[20:21], v[20:21], v[32:33] op_sel_hi:[1,0]
	v_pk_mul_f32 v[18:19], v[18:19], v[32:33] op_sel_hi:[1,0]
	v_pk_mul_f32 v[16:17], v[16:17], v[32:33] op_sel_hi:[1,0]
	v_pk_mul_f32 v[30:31], v[2:3], v[30:31]
	v_pk_mul_f32 v[28:29], v[0:1], v[28:29]
	v_pk_mul_f32 v[26:27], v[6:7], v[26:27]
	v_pk_mul_f32 v[24:25], v[4:5], v[24:25]
	v_pk_mul_f32 v[22:23], v[10:11], v[22:23]
	v_pk_mul_f32 v[20:21], v[8:9], v[20:21]
	v_pk_mul_f32 v[18:19], v[14:15], v[18:19]
	v_pk_mul_f32 v[16:17], v[12:13], v[16:17]
	global_store_dwordx4 v[34:35], v[28:31], off sc1
	global_store_dwordx4 v[34:35], v[24:27], off offset:1024 sc1
	global_store_dwordx4 v[34:35], v[20:23], off offset:2048 sc1
	global_store_dwordx4 v[34:35], v[16:19], off offset:3072 sc1
	s_branch .LBB0_411
